# ph3 rebalance + chain counted vmcnt; EpiRes (ph8,11,13) epilogue rewritten: LDS transpose to row-friendly 16B accesses
# speedup vs baseline: 1.0356x; 1.0356x over previous
.LBB0_1025:
	s_ashr_i32 s5, s4, 31
	s_add_u32 s48, s6, s48
	s_addc_u32 s49, s7, s49
	v_lshl_add_u64 v[70:71], s[48:49], 0, v[122:123]
	v_mov_b32_e32 v133, v123
	v_lshl_add_u64 v[70:71], v[70:71], 0, v[132:133]
	s_lshl_b32 s12, s10, 1
	global_load_dwordx4 v[100:103], v[70:71], off
	global_load_dwordx4 v[96:99], v[70:71], off offset:64
	global_load_dwordx4 v[92:95], v[70:71], off offset:128
	global_load_dwordx4 v[88:91], v[70:71], off offset:192
	global_load_dwordx4 v[80:83], v[68:69], off
	v_lshl_add_u64 v[68:69], v[68:69], 0, s[12:13]
	global_load_dwordx4 v[84:87], v[68:69], off
	v_lshl_add_u64 v[68:69], v[142:143], 1, s[6:7]
	v_lshl_add_u64 v[68:69], v[68:69], 0, v[132:133]
	s_lshl_b64 s[4:5], s[4:5], 2
	v_lshl_add_u64 v[72:73], v[68:69], 0, s[20:21]
	v_add_co_u32_e32 v68, vcc, s56, v68
	s_add_u32 s4, s65, s4
	s_nop 0
	v_addc_co_u32_e32 v69, vcc, 0, v69, vcc
	s_addc_u32 s5, s66, s5
	global_load_dwordx4 v[68:71], v[68:69], off
	s_nop 0
	global_load_dwordx4 v[72:75], v[72:73], off offset:64
	s_nop 0
	global_load_dword v148, v123, s[4:5]
	v_add_u32_e32 v150, v129, v127
	ds_read_b128 v[104:107], v150
	ds_read_b128 v[108:111], v150 offset:64
	ds_read_b128 v[112:115], v150 offset:4352
	ds_read_b128 v[116:119], v150 offset:4416
	s_andn2_b64 vcc, exec, s[40:41]
	s_waitcnt vmcnt(18) lgkmcnt(0)
	v_mfma_f32_16x16x32_bf16 v[104:107], v[28:31], v[104:107], 0
	v_mfma_f32_16x16x32_bf16 v[28:31], v[28:31], v[112:115], 0
	v_mfma_f32_16x16x32_bf16 v[104:107], v[24:27], v[108:111], v[104:107]
	v_mfma_f32_16x16x32_bf16 v[24:27], v[24:27], v[116:119], v[28:31]
	s_nop 5
	ds_read_b128 v[28:31], v150 offset:128
	ds_read_b128 v[108:111], v150 offset:192
	s_waitcnt lgkmcnt(1)
	v_mfma_f32_16x16x32_bf16 v[28:31], v[20:23], v[28:31], v[104:107]
	s_nop 2
	ds_read_b128 v[104:107], v150 offset:4480
	ds_read_b128 v[112:115], v150 offset:4544
	s_waitcnt lgkmcnt(1)
	v_mfma_f32_16x16x32_bf16 v[20:23], v[20:23], v[104:107], v[24:27]
	v_mfma_f32_16x16x32_bf16 v[24:27], v[16:19], v[108:111], v[28:31]
	s_waitcnt lgkmcnt(0)
	v_mfma_f32_16x16x32_bf16 v[16:19], v[16:19], v[112:115], v[20:23]
	s_nop 0
	v_cndmask_b32_e64 v28, 0, 1, s[40:41]
	v_cmp_ne_u32_e64 s[4:5], 1, v28
	s_cbranch_vccnz .LBB0_1027
	s_nop 0
	v_and_b32_e32 v21, 0xffff0000, v8
	v_lshlrev_b32_e32 v20, 16, v8
	v_and_b32_e32 v23, 0xffff0000, v9
	v_lshlrev_b32_e32 v22, 16, v9
	v_pk_add_f32 v[20:21], v[20:21], v[24:25] neg_lo:[0,1] neg_hi:[0,1]
	v_pk_add_f32 v[22:23], v[22:23], v[26:27] neg_lo:[0,1] neg_hi:[0,1]
	v_cvt_pk_bf16_f32 v20, v20, v21
	v_cvt_pk_bf16_f32 v21, v22, v23
	v_add_u32_e32 v28, v131, v141
	ds_write_b64 v28, v[20:21] offset:8704
	v_and_b32_e32 v21, 0xffff0000, v12
	v_lshlrev_b32_e32 v20, 16, v12
	v_and_b32_e32 v23, 0xffff0000, v13
	v_lshlrev_b32_e32 v22, 16, v13
	v_pk_add_f32 v[20:21], v[20:21], v[16:17] neg_lo:[0,1] neg_hi:[0,1]
	v_pk_add_f32 v[22:23], v[22:23], v[18:19] neg_lo:[0,1] neg_hi:[0,1]
	v_cvt_pk_bf16_f32 v20, v20, v21
	v_cvt_pk_bf16_f32 v21, v22, v23
	ds_write_b64 v28, v[20:21] offset:11008

.LBB0_1034:
	s_ashr_i32 s11, s10, 31
	s_add_u32 s52, s48, s52
	s_addc_u32 s53, s49, s53
	v_lshl_add_u64 v[2:3], s[52:53], 0, v[122:123]
	v_mov_b32_e32 v133, v123
	v_lshl_add_u64 v[2:3], v[2:3], 0, v[132:133]
	s_lshl_b32 s12, s50, 1
	global_load_dwordx4 v[28:31], v[2:3], off
	global_load_dwordx4 v[24:27], v[2:3], off offset:64
	global_load_dwordx4 v[20:23], v[2:3], off offset:128
	global_load_dwordx4 v[16:19], v[2:3], off offset:192
	global_load_dwordx4 v[8:11], v[0:1], off
	v_lshl_add_u64 v[0:1], v[0:1], 0, s[12:13]
	global_load_dwordx4 v[12:15], v[0:1], off
	v_lshl_add_u64 v[0:1], v[142:143], 1, s[48:49]
	v_lshl_add_u64 v[0:1], v[0:1], 0, v[132:133]
	s_lshl_b64 s[10:11], s[10:11], 2
	v_lshl_add_u64 v[2:3], v[0:1], 0, s[20:21]
	v_add_co_u32_e32 v0, vcc, s56, v0
	s_add_u32 s10, s65, s10
	s_nop 0
	v_addc_co_u32_e32 v1, vcc, 0, v1, vcc
	s_addc_u32 s11, s66, s11
	global_load_dwordx4 v[4:7], v[0:1], off
	s_nop 0
	global_load_dwordx4 v[0:3], v[2:3], off offset:64
	s_nop 0
	global_load_dword v140, v123, s[10:11]
	ds_read_b128 v[104:107], v150
	ds_read_b128 v[108:111], v150 offset:64
	ds_read_b128 v[112:115], v150 offset:4352
	ds_read_b128 v[116:119], v150 offset:4416
	s_and_b64 vcc, exec, s[4:5]
	s_waitcnt vmcnt(18) lgkmcnt(3)
	v_mfma_f32_16x16x32_bf16 v[104:107], v[32:35], v[104:107], 0
	s_waitcnt lgkmcnt(1)
	v_mfma_f32_16x16x32_bf16 v[112:115], v[32:35], v[112:115], 0
	v_mfma_f32_16x16x32_bf16 v[104:107], v[36:39], v[108:111], v[104:107]
	s_waitcnt lgkmcnt(0)
	v_mfma_f32_16x16x32_bf16 v[108:111], v[36:39], v[116:119], v[112:115]
	s_nop 4
	ds_read_b128 v[112:115], v150 offset:128
	ds_read_b128 v[116:119], v150 offset:192
	s_waitcnt lgkmcnt(1)
	v_mfma_f32_16x16x32_bf16 v[104:107], v[40:43], v[112:115], v[104:107]
	ds_read_b128 v[112:115], v150 offset:4480
	ds_read_b128 v[152:155], v150 offset:4544
	s_waitcnt lgkmcnt(1)
	v_mfma_f32_16x16x32_bf16 v[112:115], v[40:43], v[112:115], v[108:111]
	v_mfma_f32_16x16x32_bf16 v[108:111], v[44:47], v[116:119], v[104:107]
	s_waitcnt lgkmcnt(0)
	v_mfma_f32_16x16x32_bf16 v[104:107], v[44:47], v[152:155], v[112:115]
	s_cbranch_vccnz .LBB0_1036
	s_nop 3
	v_and_b32_e32 v113, 0xffff0000, v48
	v_lshlrev_b32_e32 v112, 16, v48
	v_and_b32_e32 v115, 0xffff0000, v49
	v_lshlrev_b32_e32 v114, 16, v49
	v_pk_add_f32 v[112:113], v[112:113], v[108:109] neg_lo:[0,1] neg_hi:[0,1]
	v_pk_add_f32 v[114:115], v[114:115], v[110:111] neg_lo:[0,1] neg_hi:[0,1]
	v_cvt_pk_bf16_f32 v112, v112, v113
	v_cvt_pk_bf16_f32 v113, v114, v115
	v_add_u32_e32 v116, v131, v141
	ds_write_b64 v116, v[112:113] offset:8704
	v_and_b32_e32 v113, 0xffff0000, v52
	v_lshlrev_b32_e32 v112, 16, v52
	v_and_b32_e32 v115, 0xffff0000, v53
	v_lshlrev_b32_e32 v114, 16, v53
	v_pk_add_f32 v[112:113], v[112:113], v[104:105] neg_lo:[0,1] neg_hi:[0,1]
	v_pk_add_f32 v[114:115], v[114:115], v[106:107] neg_lo:[0,1] neg_hi:[0,1]
	v_cvt_pk_bf16_f32 v112, v112, v113
	v_cvt_pk_bf16_f32 v113, v114, v115
	ds_write_b64 v116, v[112:113] offset:11008

.LBB0_1044:
	s_ashr_i32 s11, s10, 31
	s_add_u32 s52, s48, s52
	s_addc_u32 s53, s49, s53
	v_lshl_add_u64 v[32:33], s[52:53], 0, v[122:123]
	v_mov_b32_e32 v133, v123
	v_lshl_add_u64 v[44:45], v[32:33], 0, v[132:133]
	v_lshl_add_u64 v[56:57], v[142:143], 1, s[48:49]
	global_load_dwordx4 v[32:35], v[44:45], off
	global_load_dwordx4 v[36:39], v[44:45], off offset:64
	global_load_dwordx4 v[40:43], v[44:45], off offset:128
	s_nop 0
	global_load_dwordx4 v[44:47], v[44:45], off offset:192
	s_nop 0
	global_load_dwordx4 v[48:51], v[52:53], off
	s_lshl_b32 s12, s50, 1
	v_lshl_add_u64 v[56:57], v[56:57], 0, v[132:133]
	s_lshl_b64 s[10:11], s[10:11], 2
	v_lshl_add_u64 v[60:61], v[56:57], 0, s[20:21]
	v_add_co_u32_e32 v56, vcc, s56, v56
	s_add_u32 s10, s65, s10
	v_lshl_add_u64 v[52:53], v[52:53], 0, s[12:13]
	v_addc_co_u32_e32 v57, vcc, 0, v57, vcc
	s_addc_u32 s11, s66, s11
	global_load_dwordx4 v[52:55], v[52:53], off
	s_nop 0
	global_load_dwordx4 v[56:59], v[56:57], off
	s_nop 0
	global_load_dwordx4 v[60:63], v[60:61], off offset:64
	s_nop 0
	global_load_dword v144, v123, s[10:11]
	ds_read_b128 v[104:107], v150
	ds_read_b128 v[108:111], v150 offset:64
	ds_read_b128 v[112:115], v150 offset:4352
	ds_read_b128 v[116:119], v150 offset:4416
	s_and_b64 vcc, exec, s[4:5]
	s_waitcnt vmcnt(18) lgkmcnt(3)
	v_mfma_f32_16x16x32_bf16 v[104:107], v[100:103], v[104:107], 0
	s_waitcnt lgkmcnt(1)
	v_mfma_f32_16x16x32_bf16 v[100:103], v[100:103], v[112:115], 0
	v_mfma_f32_16x16x32_bf16 v[104:107], v[96:99], v[108:111], v[104:107]
	s_waitcnt lgkmcnt(0)
	v_mfma_f32_16x16x32_bf16 v[96:99], v[96:99], v[116:119], v[100:103]
	s_nop 4
	ds_read_b128 v[100:103], v150 offset:128
	ds_read_b128 v[108:111], v150 offset:192
	s_waitcnt lgkmcnt(1)
	v_mfma_f32_16x16x32_bf16 v[100:103], v[92:95], v[100:103], v[104:107]
	s_nop 2
	ds_read_b128 v[104:107], v150 offset:4480
	ds_read_b128 v[112:115], v150 offset:4544
	s_waitcnt lgkmcnt(1)
	v_mfma_f32_16x16x32_bf16 v[96:99], v[92:95], v[104:107], v[96:99]
	v_mfma_f32_16x16x32_bf16 v[92:95], v[88:91], v[108:111], v[100:103]
	s_waitcnt lgkmcnt(0)
	v_mfma_f32_16x16x32_bf16 v[88:91], v[88:91], v[112:115], v[96:99]
	s_cbranch_vccnz .LBB0_1046
	s_nop 3
	v_and_b32_e32 v97, 0xffff0000, v80
	v_lshlrev_b32_e32 v96, 16, v80
	v_and_b32_e32 v99, 0xffff0000, v81
	v_lshlrev_b32_e32 v98, 16, v81
	v_pk_add_f32 v[96:97], v[96:97], v[92:93] neg_lo:[0,1] neg_hi:[0,1]
	v_pk_add_f32 v[98:99], v[98:99], v[94:95] neg_lo:[0,1] neg_hi:[0,1]
	v_cvt_pk_bf16_f32 v96, v96, v97
	v_cvt_pk_bf16_f32 v97, v98, v99
	v_add_u32_e32 v100, v131, v141
	ds_write_b64 v100, v[96:97] offset:8704
	v_and_b32_e32 v97, 0xffff0000, v84
	v_lshlrev_b32_e32 v96, 16, v84
	v_and_b32_e32 v99, 0xffff0000, v85
	v_lshlrev_b32_e32 v98, 16, v85
	v_pk_add_f32 v[96:97], v[96:97], v[88:89] neg_lo:[0,1] neg_hi:[0,1]
	v_pk_add_f32 v[98:99], v[98:99], v[90:91] neg_lo:[0,1] neg_hi:[0,1]
	v_cvt_pk_bf16_f32 v96, v96, v97
	v_cvt_pk_bf16_f32 v97, v98, v99
	ds_write_b64 v100, v[96:97] offset:11008

.LBB0_1051:
	s_cmpk_lt_i32 s94, 0x80
	s_cselect_b64 s[2:3], -1, 0
	s_xor_b64 s[4:5], s[84:85], -1
	s_or_b64 s[2:3], s[2:3], s[4:5]
	s_mov_b64 s[0:1], -1
	s_and_b64 vcc, exec, s[2:3]
	s_cbranch_vccz .LBB0_1119
	s_cmpk_gt_i32 s46, 0xa0
	s_cbranch_scc1 .LBB0_1118
	s_cmp_gt_i32 s94, 31
	s_waitcnt vmcnt(0)
	s_barrier
	s_cbranch_scc1 .LBB0_1118
	v_writelane_b32 v253, s92, 18
	s_lshl_b64 s[18:19], s[94:95], 10
	s_lshl_b64 s[20:21], s[46:47], 10
	v_writelane_b32 v253, s93, 19
	s_mul_i32 s1, s94, 0x30000
	v_writelane_b32 v253, s90, 14
	s_mul_hi_i32 s0, s94, 0x30000
	s_add_u32 s59, s1, 0x2e00000
	v_writelane_b32 v253, s91, 15
	s_addc_u32 s97, s0, 0
	s_add_i32 s0, 0, 0x400
	s_mov_b32 s22, 0x652b82fe
	s_mov_b32 s24, 0xfefa39ef
	s_mov_b32 s26, 0x3b39803f
	s_mov_b32 s28, 0x6a5dcb37
	s_mov_b32 s30, 0x11110bb3
	s_mov_b32 s34, 0x55555555
	s_mov_b32 s36, 0
	s_mov_b32 s38, 0
	s_mov_b32 s40, 0
	s_mov_b32 s50, 0x54442d18
	s_mov_b32 s60, 0x6dc9c883
	s_mov_b32 s62, 0x33145c00
	s_mov_b32 s64, 0x252049c0
	s_mov_b32 s66, 0
	s_mov_b32 s70, 0
	s_mov_b32 s72, 0x9037ab78
	s_mov_b32 s74, 0x46cc5e42
	s_mov_b32 s76, 0xa17f65f6
	s_mov_b32 s78, 0x19f4ec90
	s_mov_b32 s80, 0x16c16967
	s_mov_b32 s82, 0xb42fdfa7
	s_mov_b32 s84, 0xf9a43bb8
	s_mov_b32 s86, 0x796cde01
	s_mov_b32 s88, 0x19e83e5c
	v_writelane_b32 v253, s0, 20
	v_mov_b32_e32 v8, 0
	s_mov_b32 s23, 0x3ff71547
	s_mov_b32 s25, 0xbfe62e42
	s_mov_b32 s27, 0xbc7abc9e
	s_mov_b32 s29, 0x3e5ade15
	s_mov_b32 s31, 0x3f811111
	s_mov_b32 s35, 0x3fa55555
	s_mov_b32 s37, 0x41d00000
	s_mov_b32 s39, 0x7b000000
	s_movk_i32 s2, 0xff80
	s_mov_b32 s41, 0x7ff00000
	s_mov_b32 s43, 0x3ff921fb
	s_mov_b32 s51, 0xbff921fb
	s_mov_b32 s53, 0x3c91a626
	s_mov_b32 s54, 0x33145c07
	s_mov_b32 s61, 0x3fe45f30
	s_mov_b32 s63, 0xbc91a626
	s_mov_b32 s65, 0xb97b839a
	s_mov_b32 s67, 0x40900000
	s_mov_b32 s71, 0xc090cc00
	s_mov_b32 s73, 0x3e21eeb6
	s_mov_b32 s75, 0xbda907db
	s_mov_b32 s77, 0xbe927e4f
	s_mov_b32 s79, 0x3efa01a0
	s_mov_b32 s81, 0xbf56c16c
	s_mov_b32 s83, 0xbe5ae600
	s_mov_b32 s85, 0x3de5e0b2
	s_mov_b32 s87, 0x3ec71de3
	s_mov_b32 s89, 0xbf2a01a0
	s_mov_b32 s91, 0xbfc55555
	s_brev_b32 s3, 1
	s_movk_i32 s33, 0x1f8
	s_movk_i32 s56, 0x1ff
	s_add_i32 s57, 0, 0x8400
	s_mov_b64 s[92:93], 0x800
	s_add_i32 s96, 0, 0x2200
	v_mov_b32_e32 v10, 0xfca7ab0c
	v_mov_b32_e32 v11, 0x3e928af3
	v_mov_b32_e32 v12, 0x623fde64
	v_mov_b32_e32 v13, 0x3ec71dee
	v_mov_b32_e32 v14, 0x7c89e6b0
	v_mov_b32_e32 v15, 0x3efa0199
	v_mov_b32_e32 v16, 0x14761f6e
	v_mov_b32_e32 v17, 0x3f2a01a0
	v_mov_b32_e32 v18, 0x1852b7b0
	v_mov_b32_e32 v19, 0x3f56c16c
	v_mov_b32_e32 v20, 0x11122322
	v_mov_b32_e32 v21, 0x3f811111
	v_mov_b32_e32 v22, 0x555502a1
	v_mov_b32_e32 v23, 0x3fa55555
	v_mov_b32_e32 v24, 0x55555511
	v_mov_b32_e32 v25, 0x3fc55555
	v_mov_b32_e32 v26, 11
	v_mov_b32_e32 v27, 0x3fe00000
	v_mov_b32_e32 v48, 0x7ff00000
	v_mov_b32_e32 v49, 0x40100000
	v_mov_b32_e32 v50, 0x3ff00000
	v_mov_b32_e32 v51, 0x7ff80000
	v_writelane_b32 v253, s94, 16
	s_nop 1
	v_writelane_b32 v253, s95, 17
	s_branch .LBB0_1056

.LBB0_1183:
	s_cmpk_gt_i32 s94, 0x14df
	s_cbranch_scc1 .LBB0_1284
	s_load_dwordx4 s[8:11], s[16:17], 0x40
	s_add_i32 s2, s94, 0x1f0
	s_add_i32 s3, s46, 0xffffff60
	v_mov_b32_e32 v1, 0
	s_movk_i32 s31, 0x104
	s_waitcnt lgkmcnt(0)
	s_add_u32 s0, s10, 0x1000
	s_addc_u32 s1, s11, 0
	s_add_u32 s8, s8, 0x1000
	s_addc_u32 s9, s9, 0
	s_add_i32 s30, s94, 0xffffede0
	s_movk_i32 s33, 0xff00
	s_movk_i32 s101, 0x124f
	s_cmpk_lt_i32 s94, 0xa0
	s_cbranch_scc0 .Lwt3_cls_done
	s_add_i32 s2, s94, 0x11d0
	s_movk_i32 s3, 32
	s_add_i32 s30, s94, 0xfffffdc0
	s_movk_i32 s101, 0x16cf

.LBB0_1185:
	s_or_b64 exec, exec, s[4:5]
	s_add_i32 s30, s30, s3
	s_add_i32 s2, s3, s2
	s_add_i32 s4, s30, 0x1410
	s_cmp_gt_i32 s4, s101
	s_barrier
	s_cbranch_scc1 .LBB0_1284

.LBB0_1521:
	v_and_b32_e32 v146, 63, v180
	v_and_b32_e32 v147, 15, v180
	v_bfe_u32 v148, v180, 4, 2
	v_lshrrev_b32_e32 v149, 6, v180
	v_lshlrev_b32_e32 v149, 12, v149
	v_add_u32_e32 v149, 0x20000, v149
	v_and_b32_e32 v150, 7, v147
	v_xor_b32_e32 v150, v148, v150
	v_lshlrev_b32_e32 v150, 4, v150
	v_lshl_add_u32 v150, v147, 8, v150
	v_add_u32_e32 v140, v149, v150
	v_xor_b32_e32 v141, 64, v140
	v_lshrrev_b32_e32 v151, 2, v146
	v_and_b32_e32 v152, 3, v146
	v_and_b32_e32 v153, 7, v151
	v_lshlrev_b32_e32 v154, 1, v152
	v_xor_b32_e32 v154, v154, v153
	v_lshlrev_b32_e32 v154, 4, v154
	v_lshl_add_u32 v154, v151, 8, v154
	v_add_u32_e32 v142, v149, v154
	v_xor_b32_e32 v143, 16, v142
	s_lshl_b32 s24, s55, 8
	s_add_i32 s24, s24, s44
	v_add_u32_e32 v155, s24, v151
	v_lshlrev_b32_e32 v145, 2, v155
	v_lshlrev_b32_e32 v155, 11, v155
	s_lshl_b32 s24, s54, 8
	s_add_i32 s24, s24, s45
	v_lshl_add_u32 v156, v152, 3, s24
	v_lshl_add_u32 v144, v156, 1, v155
	v_cmp_eq_u32_e32 vcc, 0, v152
	s_mov_b64 s[98:99], s[12:13]
	global_load_dwordx4 v[188:191], v144, s[98:99]
	global_load_dwordx4 v[192:195], v144, s[98:99] offset:256
	s_add_u32 s98, s98, 0x8000
	s_addc_u32 s99, s99, 0
	global_load_dwordx4 v[196:199], v144, s[98:99]
	global_load_dwordx4 v[200:203], v144, s[98:99] offset:256
	s_add_u32 s98, s98, 0x8000
	s_addc_u32 s99, s99, 0
	global_load_dwordx4 v[204:207], v144, s[98:99]
	global_load_dwordx4 v[208:211], v144, s[98:99] offset:256
	s_add_u32 s98, s98, 0x8000
	s_addc_u32 s99, s99, 0
	global_load_dwordx4 v[212:215], v144, s[98:99]
	global_load_dwordx4 v[216:219], v144, s[98:99] offset:256
	s_add_u32 s98, s98, 0x28000
	s_addc_u32 s99, s99, 0
	global_load_dwordx4 v[220:223], v144, s[98:99]
	global_load_dwordx4 v[224:227], v144, s[98:99] offset:256
	s_add_u32 s98, s98, 0x8000
	s_addc_u32 s99, s99, 0
	global_load_dwordx4 v[228:231], v144, s[98:99]
	global_load_dwordx4 v[232:235], v144, s[98:99] offset:256
	s_add_u32 s98, s98, 0x8000
	s_addc_u32 s99, s99, 0
	global_load_dwordx4 v[236:239], v144, s[98:99]
	global_load_dwordx4 v[240:243], v144, s[98:99] offset:256
	s_add_u32 s98, s98, 0x8000
	s_addc_u32 s99, s99, 0
	global_load_dwordx4 v[244:247], v144, s[98:99]
	global_load_dwordx4 v[248:251], v144, s[98:99] offset:256
	s_mov_b64 s[24:25], exec
	s_mov_b64 s[98:99], s[12:13]
	ds_write_b128 v140, v[124:127]
	ds_write_b128 v141, v[120:123]
	ds_write_b128 v140, v[116:119] offset:128
	ds_write_b128 v141, v[112:115] offset:128
	s_waitcnt lgkmcnt(0)
	ds_read_b128 v[146:149], v142
	ds_read_b128 v[150:153], v143
	ds_read_b128 v[154:157], v142 offset:128
	ds_read_b128 v[158:161], v143 offset:128
	s_waitcnt vmcnt(14)
	s_waitcnt lgkmcnt(0)
	v_lshlrev_b32_e32 v162, 16, v188
	v_and_b32_e32 v163, 0xffff0000, v188
	v_lshlrev_b32_e32 v164, 16, v189
	v_and_b32_e32 v165, 0xffff0000, v189
	v_lshlrev_b32_e32 v166, 16, v190
	v_and_b32_e32 v167, 0xffff0000, v190
	v_lshlrev_b32_e32 v168, 16, v191
	v_and_b32_e32 v169, 0xffff0000, v191
	v_pk_add_f32 v[146:147], v[146:147], v[162:163]
	v_pk_add_f32 v[148:149], v[148:149], v[164:165]
	v_pk_add_f32 v[150:151], v[150:151], v[166:167]
	v_pk_add_f32 v[152:153], v[152:153], v[168:169]
	v_pk_mul_f32 v[170:171], v[146:147], v[146:147]
	v_pk_fma_f32 v[170:171], v[148:149], v[148:149], v[170:171]
	v_pk_fma_f32 v[170:171], v[150:151], v[150:151], v[170:171]
	v_pk_fma_f32 v[170:171], v[152:153], v[152:153], v[170:171]
	v_cvt_pk_bf16_f32 v172, v146, v147
	v_cvt_pk_bf16_f32 v173, v148, v149
	v_cvt_pk_bf16_f32 v174, v150, v151
	v_cvt_pk_bf16_f32 v175, v152, v153
	global_store_dwordx4 v144, v[172:175], s[98:99]
	v_lshlrev_b32_e32 v162, 16, v192
	v_and_b32_e32 v163, 0xffff0000, v192
	v_lshlrev_b32_e32 v164, 16, v193
	v_and_b32_e32 v165, 0xffff0000, v193
	v_lshlrev_b32_e32 v166, 16, v194
	v_and_b32_e32 v167, 0xffff0000, v194
	v_lshlrev_b32_e32 v168, 16, v195
	v_and_b32_e32 v169, 0xffff0000, v195
	v_pk_add_f32 v[154:155], v[154:155], v[162:163]
	v_pk_add_f32 v[156:157], v[156:157], v[164:165]
	v_pk_add_f32 v[158:159], v[158:159], v[166:167]
	v_pk_add_f32 v[160:161], v[160:161], v[168:169]
	v_pk_fma_f32 v[170:171], v[154:155], v[154:155], v[170:171]
	v_pk_fma_f32 v[170:171], v[156:157], v[156:157], v[170:171]
	v_pk_fma_f32 v[170:171], v[158:159], v[158:159], v[170:171]
	v_pk_fma_f32 v[170:171], v[160:161], v[160:161], v[170:171]
	v_cvt_pk_bf16_f32 v176, v154, v155
	v_cvt_pk_bf16_f32 v177, v156, v157
	v_cvt_pk_bf16_f32 v178, v158, v159
	v_cvt_pk_bf16_f32 v179, v160, v161
	global_store_dwordx4 v144, v[176:179], s[98:99] offset:256
	v_add_f32_e32 v162, v170, v171
	s_nop 1
	v_add_f32_dpp v163, v162, v162 quad_perm:[1,0,3,2] row_mask:0xf bank_mask:0xf
	s_nop 1
	v_add_f32_dpp v164, v163, v163 quad_perm:[2,3,0,1] row_mask:0xf bank_mask:0xf
	s_mov_b64 exec, vcc
	global_atomic_add_f32 v145, v164, s[14:15] offset:0
	s_mov_b64 exec, s[24:25]
	s_add_u32 s98, s98, 0x8000
	s_addc_u32 s99, s99, 0
	ds_write_b128 v140, v[108:111]
	ds_write_b128 v141, v[104:107]
	ds_write_b128 v140, v[100:103] offset:128
	ds_write_b128 v141, v[96:99] offset:128
	s_waitcnt lgkmcnt(0)
	ds_read_b128 v[146:149], v142
	ds_read_b128 v[150:153], v143
	ds_read_b128 v[154:157], v142 offset:128
	ds_read_b128 v[158:161], v143 offset:128
	s_waitcnt vmcnt(15)
	s_waitcnt lgkmcnt(0)
	v_lshlrev_b32_e32 v162, 16, v196
	v_and_b32_e32 v163, 0xffff0000, v196
	v_lshlrev_b32_e32 v164, 16, v197
	v_and_b32_e32 v165, 0xffff0000, v197
	v_lshlrev_b32_e32 v166, 16, v198
	v_and_b32_e32 v167, 0xffff0000, v198
	v_lshlrev_b32_e32 v168, 16, v199
	v_and_b32_e32 v169, 0xffff0000, v199
	v_pk_add_f32 v[146:147], v[146:147], v[162:163]
	v_pk_add_f32 v[148:149], v[148:149], v[164:165]
	v_pk_add_f32 v[150:151], v[150:151], v[166:167]
	v_pk_add_f32 v[152:153], v[152:153], v[168:169]
	v_pk_mul_f32 v[170:171], v[146:147], v[146:147]
	v_pk_fma_f32 v[170:171], v[148:149], v[148:149], v[170:171]
	v_pk_fma_f32 v[170:171], v[150:151], v[150:151], v[170:171]
	v_pk_fma_f32 v[170:171], v[152:153], v[152:153], v[170:171]
	v_cvt_pk_bf16_f32 v172, v146, v147
	v_cvt_pk_bf16_f32 v173, v148, v149
	v_cvt_pk_bf16_f32 v174, v150, v151
	v_cvt_pk_bf16_f32 v175, v152, v153
	global_store_dwordx4 v144, v[172:175], s[98:99]
	v_lshlrev_b32_e32 v162, 16, v200
	v_and_b32_e32 v163, 0xffff0000, v200
	v_lshlrev_b32_e32 v164, 16, v201
	v_and_b32_e32 v165, 0xffff0000, v201
	v_lshlrev_b32_e32 v166, 16, v202
	v_and_b32_e32 v167, 0xffff0000, v202
	v_lshlrev_b32_e32 v168, 16, v203
	v_and_b32_e32 v169, 0xffff0000, v203
	v_pk_add_f32 v[154:155], v[154:155], v[162:163]
	v_pk_add_f32 v[156:157], v[156:157], v[164:165]
	v_pk_add_f32 v[158:159], v[158:159], v[166:167]
	v_pk_add_f32 v[160:161], v[160:161], v[168:169]
	v_pk_fma_f32 v[170:171], v[154:155], v[154:155], v[170:171]
	v_pk_fma_f32 v[170:171], v[156:157], v[156:157], v[170:171]
	v_pk_fma_f32 v[170:171], v[158:159], v[158:159], v[170:171]
	v_pk_fma_f32 v[170:171], v[160:161], v[160:161], v[170:171]
	v_cvt_pk_bf16_f32 v176, v154, v155
	v_cvt_pk_bf16_f32 v177, v156, v157
	v_cvt_pk_bf16_f32 v178, v158, v159
	v_cvt_pk_bf16_f32 v179, v160, v161
	global_store_dwordx4 v144, v[176:179], s[98:99] offset:256
	v_add_f32_e32 v162, v170, v171
	s_nop 1
	v_add_f32_dpp v163, v162, v162 quad_perm:[1,0,3,2] row_mask:0xf bank_mask:0xf
	s_nop 1
	v_add_f32_dpp v164, v163, v163 quad_perm:[2,3,0,1] row_mask:0xf bank_mask:0xf
	s_mov_b64 exec, vcc
	global_atomic_add_f32 v145, v164, s[14:15] offset:64
	s_mov_b64 exec, s[24:25]
	s_add_u32 s98, s98, 0x8000
	s_addc_u32 s99, s99, 0
	ds_write_b128 v140, v[92:95]
	ds_write_b128 v141, v[88:91]
	ds_write_b128 v140, v[84:87] offset:128
	ds_write_b128 v141, v[80:83] offset:128
	s_waitcnt lgkmcnt(0)
	ds_read_b128 v[146:149], v142
	ds_read_b128 v[150:153], v143
	ds_read_b128 v[154:157], v142 offset:128
	ds_read_b128 v[158:161], v143 offset:128
	s_waitcnt vmcnt(16)
	s_waitcnt lgkmcnt(0)
	v_lshlrev_b32_e32 v162, 16, v204
	v_and_b32_e32 v163, 0xffff0000, v204
	v_lshlrev_b32_e32 v164, 16, v205
	v_and_b32_e32 v165, 0xffff0000, v205
	v_lshlrev_b32_e32 v166, 16, v206
	v_and_b32_e32 v167, 0xffff0000, v206
	v_lshlrev_b32_e32 v168, 16, v207
	v_and_b32_e32 v169, 0xffff0000, v207
	v_pk_add_f32 v[146:147], v[146:147], v[162:163]
	v_pk_add_f32 v[148:149], v[148:149], v[164:165]
	v_pk_add_f32 v[150:151], v[150:151], v[166:167]
	v_pk_add_f32 v[152:153], v[152:153], v[168:169]
	v_pk_mul_f32 v[170:171], v[146:147], v[146:147]
	v_pk_fma_f32 v[170:171], v[148:149], v[148:149], v[170:171]
	v_pk_fma_f32 v[170:171], v[150:151], v[150:151], v[170:171]
	v_pk_fma_f32 v[170:171], v[152:153], v[152:153], v[170:171]
	v_cvt_pk_bf16_f32 v172, v146, v147
	v_cvt_pk_bf16_f32 v173, v148, v149
	v_cvt_pk_bf16_f32 v174, v150, v151
	v_cvt_pk_bf16_f32 v175, v152, v153
	global_store_dwordx4 v144, v[172:175], s[98:99]
	v_lshlrev_b32_e32 v162, 16, v208
	v_and_b32_e32 v163, 0xffff0000, v208
	v_lshlrev_b32_e32 v164, 16, v209
	v_and_b32_e32 v165, 0xffff0000, v209
	v_lshlrev_b32_e32 v166, 16, v210
	v_and_b32_e32 v167, 0xffff0000, v210
	v_lshlrev_b32_e32 v168, 16, v211
	v_and_b32_e32 v169, 0xffff0000, v211
	v_pk_add_f32 v[154:155], v[154:155], v[162:163]
	v_pk_add_f32 v[156:157], v[156:157], v[164:165]
	v_pk_add_f32 v[158:159], v[158:159], v[166:167]
	v_pk_add_f32 v[160:161], v[160:161], v[168:169]
	v_pk_fma_f32 v[170:171], v[154:155], v[154:155], v[170:171]
	v_pk_fma_f32 v[170:171], v[156:157], v[156:157], v[170:171]
	v_pk_fma_f32 v[170:171], v[158:159], v[158:159], v[170:171]
	v_pk_fma_f32 v[170:171], v[160:161], v[160:161], v[170:171]
	v_cvt_pk_bf16_f32 v176, v154, v155
	v_cvt_pk_bf16_f32 v177, v156, v157
	v_cvt_pk_bf16_f32 v178, v158, v159
	v_cvt_pk_bf16_f32 v179, v160, v161
	global_store_dwordx4 v144, v[176:179], s[98:99] offset:256
	v_add_f32_e32 v162, v170, v171
	s_nop 1
	v_add_f32_dpp v163, v162, v162 quad_perm:[1,0,3,2] row_mask:0xf bank_mask:0xf
	s_nop 1
	v_add_f32_dpp v164, v163, v163 quad_perm:[2,3,0,1] row_mask:0xf bank_mask:0xf
	s_mov_b64 exec, vcc
	global_atomic_add_f32 v145, v164, s[14:15] offset:128
	s_mov_b64 exec, s[24:25]
	s_add_u32 s98, s98, 0x8000
	s_addc_u32 s99, s99, 0
	ds_write_b128 v140, v[76:79]
	ds_write_b128 v141, v[72:75]
	ds_write_b128 v140, v[68:71] offset:128
	ds_write_b128 v141, v[64:67] offset:128
	s_waitcnt lgkmcnt(0)
	ds_read_b128 v[146:149], v142
	ds_read_b128 v[150:153], v143
	ds_read_b128 v[154:157], v142 offset:128
	ds_read_b128 v[158:161], v143 offset:128
	s_waitcnt vmcnt(17)
	s_waitcnt lgkmcnt(0)
	v_lshlrev_b32_e32 v162, 16, v212
	v_and_b32_e32 v163, 0xffff0000, v212
	v_lshlrev_b32_e32 v164, 16, v213
	v_and_b32_e32 v165, 0xffff0000, v213
	v_lshlrev_b32_e32 v166, 16, v214
	v_and_b32_e32 v167, 0xffff0000, v214
	v_lshlrev_b32_e32 v168, 16, v215
	v_and_b32_e32 v169, 0xffff0000, v215
	v_pk_add_f32 v[146:147], v[146:147], v[162:163]
	v_pk_add_f32 v[148:149], v[148:149], v[164:165]
	v_pk_add_f32 v[150:151], v[150:151], v[166:167]
	v_pk_add_f32 v[152:153], v[152:153], v[168:169]
	v_pk_mul_f32 v[170:171], v[146:147], v[146:147]
	v_pk_fma_f32 v[170:171], v[148:149], v[148:149], v[170:171]
	v_pk_fma_f32 v[170:171], v[150:151], v[150:151], v[170:171]
	v_pk_fma_f32 v[170:171], v[152:153], v[152:153], v[170:171]
	v_cvt_pk_bf16_f32 v172, v146, v147
	v_cvt_pk_bf16_f32 v173, v148, v149
	v_cvt_pk_bf16_f32 v174, v150, v151
	v_cvt_pk_bf16_f32 v175, v152, v153
	global_store_dwordx4 v144, v[172:175], s[98:99]
	v_lshlrev_b32_e32 v162, 16, v216
	v_and_b32_e32 v163, 0xffff0000, v216
	v_lshlrev_b32_e32 v164, 16, v217
	v_and_b32_e32 v165, 0xffff0000, v217
	v_lshlrev_b32_e32 v166, 16, v218
	v_and_b32_e32 v167, 0xffff0000, v218
	v_lshlrev_b32_e32 v168, 16, v219
	v_and_b32_e32 v169, 0xffff0000, v219
	v_pk_add_f32 v[154:155], v[154:155], v[162:163]
	v_pk_add_f32 v[156:157], v[156:157], v[164:165]
	v_pk_add_f32 v[158:159], v[158:159], v[166:167]
	v_pk_add_f32 v[160:161], v[160:161], v[168:169]
	v_pk_fma_f32 v[170:171], v[154:155], v[154:155], v[170:171]
	v_pk_fma_f32 v[170:171], v[156:157], v[156:157], v[170:171]
	v_pk_fma_f32 v[170:171], v[158:159], v[158:159], v[170:171]
	v_pk_fma_f32 v[170:171], v[160:161], v[160:161], v[170:171]
	v_cvt_pk_bf16_f32 v176, v154, v155
	v_cvt_pk_bf16_f32 v177, v156, v157
	v_cvt_pk_bf16_f32 v178, v158, v159
	v_cvt_pk_bf16_f32 v179, v160, v161
	global_store_dwordx4 v144, v[176:179], s[98:99] offset:256
	v_add_f32_e32 v162, v170, v171
	s_nop 1
	v_add_f32_dpp v163, v162, v162 quad_perm:[1,0,3,2] row_mask:0xf bank_mask:0xf
	s_nop 1
	v_add_f32_dpp v164, v163, v163 quad_perm:[2,3,0,1] row_mask:0xf bank_mask:0xf
	s_mov_b64 exec, vcc
	global_atomic_add_f32 v145, v164, s[14:15] offset:192
	s_mov_b64 exec, s[24:25]
	s_add_u32 s98, s98, 0x28000
	s_addc_u32 s99, s99, 0
	ds_write_b128 v140, v[60:63]
	ds_write_b128 v141, v[56:59]
	ds_write_b128 v140, v[52:55] offset:128
	ds_write_b128 v141, v[48:51] offset:128
	s_waitcnt lgkmcnt(0)
	ds_read_b128 v[146:149], v142
	ds_read_b128 v[150:153], v143
	ds_read_b128 v[154:157], v142 offset:128
	ds_read_b128 v[158:161], v143 offset:128
	s_waitcnt vmcnt(18)
	s_waitcnt lgkmcnt(0)
	v_lshlrev_b32_e32 v162, 16, v220
	v_and_b32_e32 v163, 0xffff0000, v220
	v_lshlrev_b32_e32 v164, 16, v221
	v_and_b32_e32 v165, 0xffff0000, v221
	v_lshlrev_b32_e32 v166, 16, v222
	v_and_b32_e32 v167, 0xffff0000, v222
	v_lshlrev_b32_e32 v168, 16, v223
	v_and_b32_e32 v169, 0xffff0000, v223
	v_pk_add_f32 v[146:147], v[146:147], v[162:163]
	v_pk_add_f32 v[148:149], v[148:149], v[164:165]
	v_pk_add_f32 v[150:151], v[150:151], v[166:167]
	v_pk_add_f32 v[152:153], v[152:153], v[168:169]
	v_pk_mul_f32 v[170:171], v[146:147], v[146:147]
	v_pk_fma_f32 v[170:171], v[148:149], v[148:149], v[170:171]
	v_pk_fma_f32 v[170:171], v[150:151], v[150:151], v[170:171]
	v_pk_fma_f32 v[170:171], v[152:153], v[152:153], v[170:171]
	v_cvt_pk_bf16_f32 v172, v146, v147
	v_cvt_pk_bf16_f32 v173, v148, v149
	v_cvt_pk_bf16_f32 v174, v150, v151
	v_cvt_pk_bf16_f32 v175, v152, v153
	global_store_dwordx4 v144, v[172:175], s[98:99]
	v_lshlrev_b32_e32 v162, 16, v224
	v_and_b32_e32 v163, 0xffff0000, v224
	v_lshlrev_b32_e32 v164, 16, v225
	v_and_b32_e32 v165, 0xffff0000, v225
	v_lshlrev_b32_e32 v166, 16, v226
	v_and_b32_e32 v167, 0xffff0000, v226
	v_lshlrev_b32_e32 v168, 16, v227
	v_and_b32_e32 v169, 0xffff0000, v227
	v_pk_add_f32 v[154:155], v[154:155], v[162:163]
	v_pk_add_f32 v[156:157], v[156:157], v[164:165]
	v_pk_add_f32 v[158:159], v[158:159], v[166:167]
	v_pk_add_f32 v[160:161], v[160:161], v[168:169]
	v_pk_fma_f32 v[170:171], v[154:155], v[154:155], v[170:171]
	v_pk_fma_f32 v[170:171], v[156:157], v[156:157], v[170:171]
	v_pk_fma_f32 v[170:171], v[158:159], v[158:159], v[170:171]
	v_pk_fma_f32 v[170:171], v[160:161], v[160:161], v[170:171]
	v_cvt_pk_bf16_f32 v176, v154, v155
	v_cvt_pk_bf16_f32 v177, v156, v157
	v_cvt_pk_bf16_f32 v178, v158, v159
	v_cvt_pk_bf16_f32 v179, v160, v161
	global_store_dwordx4 v144, v[176:179], s[98:99] offset:256
	v_add_f32_e32 v162, v170, v171
	s_nop 1
	v_add_f32_dpp v163, v162, v162 quad_perm:[1,0,3,2] row_mask:0xf bank_mask:0xf
	s_nop 1
	v_add_f32_dpp v164, v163, v163 quad_perm:[2,3,0,1] row_mask:0xf bank_mask:0xf
	s_mov_b64 exec, vcc
	global_atomic_add_f32 v145, v164, s[14:15] offset:512
	s_mov_b64 exec, s[24:25]
	s_add_u32 s98, s98, 0x8000
	s_addc_u32 s99, s99, 0
	ds_write_b128 v140, v[44:47]
	ds_write_b128 v141, v[40:43]
	ds_write_b128 v140, v[36:39] offset:128
	ds_write_b128 v141, v[32:35] offset:128
	s_waitcnt lgkmcnt(0)
	ds_read_b128 v[146:149], v142
	ds_read_b128 v[150:153], v143
	ds_read_b128 v[154:157], v142 offset:128
	ds_read_b128 v[158:161], v143 offset:128
	s_waitcnt vmcnt(19)
	s_waitcnt lgkmcnt(0)
	v_lshlrev_b32_e32 v162, 16, v228
	v_and_b32_e32 v163, 0xffff0000, v228
	v_lshlrev_b32_e32 v164, 16, v229
	v_and_b32_e32 v165, 0xffff0000, v229
	v_lshlrev_b32_e32 v166, 16, v230
	v_and_b32_e32 v167, 0xffff0000, v230
	v_lshlrev_b32_e32 v168, 16, v231
	v_and_b32_e32 v169, 0xffff0000, v231
	v_pk_add_f32 v[146:147], v[146:147], v[162:163]
	v_pk_add_f32 v[148:149], v[148:149], v[164:165]
	v_pk_add_f32 v[150:151], v[150:151], v[166:167]
	v_pk_add_f32 v[152:153], v[152:153], v[168:169]
	v_pk_mul_f32 v[170:171], v[146:147], v[146:147]
	v_pk_fma_f32 v[170:171], v[148:149], v[148:149], v[170:171]
	v_pk_fma_f32 v[170:171], v[150:151], v[150:151], v[170:171]
	v_pk_fma_f32 v[170:171], v[152:153], v[152:153], v[170:171]
	v_cvt_pk_bf16_f32 v172, v146, v147
	v_cvt_pk_bf16_f32 v173, v148, v149
	v_cvt_pk_bf16_f32 v174, v150, v151
	v_cvt_pk_bf16_f32 v175, v152, v153
	global_store_dwordx4 v144, v[172:175], s[98:99]
	v_lshlrev_b32_e32 v162, 16, v232
	v_and_b32_e32 v163, 0xffff0000, v232
	v_lshlrev_b32_e32 v164, 16, v233
	v_and_b32_e32 v165, 0xffff0000, v233
	v_lshlrev_b32_e32 v166, 16, v234
	v_and_b32_e32 v167, 0xffff0000, v234
	v_lshlrev_b32_e32 v168, 16, v235
	v_and_b32_e32 v169, 0xffff0000, v235
	v_pk_add_f32 v[154:155], v[154:155], v[162:163]
	v_pk_add_f32 v[156:157], v[156:157], v[164:165]
	v_pk_add_f32 v[158:159], v[158:159], v[166:167]
	v_pk_add_f32 v[160:161], v[160:161], v[168:169]
	v_pk_fma_f32 v[170:171], v[154:155], v[154:155], v[170:171]
	v_pk_fma_f32 v[170:171], v[156:157], v[156:157], v[170:171]
	v_pk_fma_f32 v[170:171], v[158:159], v[158:159], v[170:171]
	v_pk_fma_f32 v[170:171], v[160:161], v[160:161], v[170:171]
	v_cvt_pk_bf16_f32 v176, v154, v155
	v_cvt_pk_bf16_f32 v177, v156, v157
	v_cvt_pk_bf16_f32 v178, v158, v159
	v_cvt_pk_bf16_f32 v179, v160, v161
	global_store_dwordx4 v144, v[176:179], s[98:99] offset:256
	v_add_f32_e32 v162, v170, v171
	s_nop 1
	v_add_f32_dpp v163, v162, v162 quad_perm:[1,0,3,2] row_mask:0xf bank_mask:0xf
	s_nop 1
	v_add_f32_dpp v164, v163, v163 quad_perm:[2,3,0,1] row_mask:0xf bank_mask:0xf
	s_mov_b64 exec, vcc
	global_atomic_add_f32 v145, v164, s[14:15] offset:576
	s_mov_b64 exec, s[24:25]
	s_add_u32 s98, s98, 0x8000
	s_addc_u32 s99, s99, 0
	ds_write_b128 v140, v[28:31]
	ds_write_b128 v141, v[24:27]
	ds_write_b128 v140, v[20:23] offset:128
	ds_write_b128 v141, v[16:19] offset:128
	s_waitcnt lgkmcnt(0)
	ds_read_b128 v[146:149], v142
	ds_read_b128 v[150:153], v143
	ds_read_b128 v[154:157], v142 offset:128
	ds_read_b128 v[158:161], v143 offset:128
	s_waitcnt vmcnt(20)
	s_waitcnt lgkmcnt(0)
	v_lshlrev_b32_e32 v162, 16, v236
	v_and_b32_e32 v163, 0xffff0000, v236
	v_lshlrev_b32_e32 v164, 16, v237
	v_and_b32_e32 v165, 0xffff0000, v237
	v_lshlrev_b32_e32 v166, 16, v238
	v_and_b32_e32 v167, 0xffff0000, v238
	v_lshlrev_b32_e32 v168, 16, v239
	v_and_b32_e32 v169, 0xffff0000, v239
	v_pk_add_f32 v[146:147], v[146:147], v[162:163]
	v_pk_add_f32 v[148:149], v[148:149], v[164:165]
	v_pk_add_f32 v[150:151], v[150:151], v[166:167]
	v_pk_add_f32 v[152:153], v[152:153], v[168:169]
	v_pk_mul_f32 v[170:171], v[146:147], v[146:147]
	v_pk_fma_f32 v[170:171], v[148:149], v[148:149], v[170:171]
	v_pk_fma_f32 v[170:171], v[150:151], v[150:151], v[170:171]
	v_pk_fma_f32 v[170:171], v[152:153], v[152:153], v[170:171]
	v_cvt_pk_bf16_f32 v172, v146, v147
	v_cvt_pk_bf16_f32 v173, v148, v149
	v_cvt_pk_bf16_f32 v174, v150, v151
	v_cvt_pk_bf16_f32 v175, v152, v153
	global_store_dwordx4 v144, v[172:175], s[98:99]
	v_lshlrev_b32_e32 v162, 16, v240
	v_and_b32_e32 v163, 0xffff0000, v240
	v_lshlrev_b32_e32 v164, 16, v241
	v_and_b32_e32 v165, 0xffff0000, v241
	v_lshlrev_b32_e32 v166, 16, v242
	v_and_b32_e32 v167, 0xffff0000, v242
	v_lshlrev_b32_e32 v168, 16, v243
	v_and_b32_e32 v169, 0xffff0000, v243
	v_pk_add_f32 v[154:155], v[154:155], v[162:163]
	v_pk_add_f32 v[156:157], v[156:157], v[164:165]
	v_pk_add_f32 v[158:159], v[158:159], v[166:167]
	v_pk_add_f32 v[160:161], v[160:161], v[168:169]
	v_pk_fma_f32 v[170:171], v[154:155], v[154:155], v[170:171]
	v_pk_fma_f32 v[170:171], v[156:157], v[156:157], v[170:171]
	v_pk_fma_f32 v[170:171], v[158:159], v[158:159], v[170:171]
	v_pk_fma_f32 v[170:171], v[160:161], v[160:161], v[170:171]
	v_cvt_pk_bf16_f32 v176, v154, v155
	v_cvt_pk_bf16_f32 v177, v156, v157
	v_cvt_pk_bf16_f32 v178, v158, v159
	v_cvt_pk_bf16_f32 v179, v160, v161
	global_store_dwordx4 v144, v[176:179], s[98:99] offset:256
	v_add_f32_e32 v162, v170, v171
	s_nop 1
	v_add_f32_dpp v163, v162, v162 quad_perm:[1,0,3,2] row_mask:0xf bank_mask:0xf
	s_nop 1
	v_add_f32_dpp v164, v163, v163 quad_perm:[2,3,0,1] row_mask:0xf bank_mask:0xf
	s_mov_b64 exec, vcc
	global_atomic_add_f32 v145, v164, s[14:15] offset:640
	s_mov_b64 exec, s[24:25]
	s_add_u32 s98, s98, 0x8000
	s_addc_u32 s99, s99, 0
	ds_write_b128 v140, v[12:15]
	ds_write_b128 v141, v[8:11]
	ds_write_b128 v140, v[4:7] offset:128
	ds_write_b128 v141, v[0:3] offset:128
	s_waitcnt lgkmcnt(0)
	ds_read_b128 v[146:149], v142
	ds_read_b128 v[150:153], v143
	ds_read_b128 v[154:157], v142 offset:128
	ds_read_b128 v[158:161], v143 offset:128
	s_waitcnt vmcnt(21)
	s_waitcnt lgkmcnt(0)
	v_lshlrev_b32_e32 v162, 16, v244
	v_and_b32_e32 v163, 0xffff0000, v244
	v_lshlrev_b32_e32 v164, 16, v245
	v_and_b32_e32 v165, 0xffff0000, v245
	v_lshlrev_b32_e32 v166, 16, v246
	v_and_b32_e32 v167, 0xffff0000, v246
	v_lshlrev_b32_e32 v168, 16, v247
	v_and_b32_e32 v169, 0xffff0000, v247
	v_pk_add_f32 v[146:147], v[146:147], v[162:163]
	v_pk_add_f32 v[148:149], v[148:149], v[164:165]
	v_pk_add_f32 v[150:151], v[150:151], v[166:167]
	v_pk_add_f32 v[152:153], v[152:153], v[168:169]
	v_pk_mul_f32 v[170:171], v[146:147], v[146:147]
	v_pk_fma_f32 v[170:171], v[148:149], v[148:149], v[170:171]
	v_pk_fma_f32 v[170:171], v[150:151], v[150:151], v[170:171]
	v_pk_fma_f32 v[170:171], v[152:153], v[152:153], v[170:171]
	v_cvt_pk_bf16_f32 v172, v146, v147
	v_cvt_pk_bf16_f32 v173, v148, v149
	v_cvt_pk_bf16_f32 v174, v150, v151
	v_cvt_pk_bf16_f32 v175, v152, v153
	global_store_dwordx4 v144, v[172:175], s[98:99]
	v_lshlrev_b32_e32 v162, 16, v248
	v_and_b32_e32 v163, 0xffff0000, v248
	v_lshlrev_b32_e32 v164, 16, v249
	v_and_b32_e32 v165, 0xffff0000, v249
	v_lshlrev_b32_e32 v166, 16, v250
	v_and_b32_e32 v167, 0xffff0000, v250
	v_lshlrev_b32_e32 v168, 16, v251
	v_and_b32_e32 v169, 0xffff0000, v251
	v_pk_add_f32 v[154:155], v[154:155], v[162:163]
	v_pk_add_f32 v[156:157], v[156:157], v[164:165]
	v_pk_add_f32 v[158:159], v[158:159], v[166:167]
	v_pk_add_f32 v[160:161], v[160:161], v[168:169]
	v_pk_fma_f32 v[170:171], v[154:155], v[154:155], v[170:171]
	v_pk_fma_f32 v[170:171], v[156:157], v[156:157], v[170:171]
	v_pk_fma_f32 v[170:171], v[158:159], v[158:159], v[170:171]
	v_pk_fma_f32 v[170:171], v[160:161], v[160:161], v[170:171]
	v_cvt_pk_bf16_f32 v176, v154, v155
	v_cvt_pk_bf16_f32 v177, v156, v157
	v_cvt_pk_bf16_f32 v178, v158, v159
	v_cvt_pk_bf16_f32 v179, v160, v161
	global_store_dwordx4 v144, v[176:179], s[98:99] offset:256
	v_add_f32_e32 v162, v170, v171
	s_nop 1
	v_add_f32_dpp v163, v162, v162 quad_perm:[1,0,3,2] row_mask:0xf bank_mask:0xf
	s_nop 1
	v_add_f32_dpp v164, v163, v163 quad_perm:[2,3,0,1] row_mask:0xf bank_mask:0xf
	s_mov_b64 exec, vcc
	global_atomic_add_f32 v145, v164, s[14:15] offset:704
	s_mov_b64 exec, s[24:25]

.LBB0_1838:
	v_and_b32_e32 v146, 63, v180
	v_and_b32_e32 v147, 15, v180
	v_bfe_u32 v148, v180, 4, 2
	v_lshrrev_b32_e32 v149, 6, v180
	v_lshlrev_b32_e32 v149, 12, v149
	v_add_u32_e32 v149, 0x20000, v149
	v_and_b32_e32 v150, 7, v147
	v_xor_b32_e32 v150, v148, v150
	v_lshlrev_b32_e32 v150, 4, v150
	v_lshl_add_u32 v150, v147, 8, v150
	v_add_u32_e32 v140, v149, v150
	v_xor_b32_e32 v141, 64, v140
	v_lshrrev_b32_e32 v151, 2, v146
	v_and_b32_e32 v152, 3, v146
	v_and_b32_e32 v153, 7, v151
	v_lshlrev_b32_e32 v154, 1, v152
	v_xor_b32_e32 v154, v154, v153
	v_lshlrev_b32_e32 v154, 4, v154
	v_lshl_add_u32 v154, v151, 8, v154
	v_add_u32_e32 v142, v149, v154
	v_xor_b32_e32 v143, 16, v142
	s_lshl_b32 s21, s30, 8
	s_add_i32 s21, s21, s51
	v_add_u32_e32 v155, s21, v151
	v_lshlrev_b32_e32 v145, 2, v155
	v_lshlrev_b32_e32 v155, 11, v155
	s_lshl_b32 s21, s28, 8
	s_add_i32 s21, s21, s52
	v_lshl_add_u32 v156, v152, 3, s21
	v_lshl_add_u32 v144, v156, 1, v155
	v_cmp_eq_u32_e32 vcc, 0, v152
	s_mov_b64 s[98:99], s[10:11]
	global_load_dwordx4 v[188:191], v144, s[98:99]
	global_load_dwordx4 v[192:195], v144, s[98:99] offset:256
	s_add_u32 s98, s98, 0x8000
	s_addc_u32 s99, s99, 0
	global_load_dwordx4 v[196:199], v144, s[98:99]
	global_load_dwordx4 v[200:203], v144, s[98:99] offset:256
	s_add_u32 s98, s98, 0x8000
	s_addc_u32 s99, s99, 0
	global_load_dwordx4 v[204:207], v144, s[98:99]
	global_load_dwordx4 v[208:211], v144, s[98:99] offset:256
	s_add_u32 s98, s98, 0x8000
	s_addc_u32 s99, s99, 0
	global_load_dwordx4 v[212:215], v144, s[98:99]
	global_load_dwordx4 v[216:219], v144, s[98:99] offset:256
	s_add_u32 s98, s98, 0x28000
	s_addc_u32 s99, s99, 0
	global_load_dwordx4 v[220:223], v144, s[98:99]
	global_load_dwordx4 v[224:227], v144, s[98:99] offset:256
	s_add_u32 s98, s98, 0x8000
	s_addc_u32 s99, s99, 0
	global_load_dwordx4 v[228:231], v144, s[98:99]
	global_load_dwordx4 v[232:235], v144, s[98:99] offset:256
	s_add_u32 s98, s98, 0x8000
	s_addc_u32 s99, s99, 0
	global_load_dwordx4 v[236:239], v144, s[98:99]
	global_load_dwordx4 v[240:243], v144, s[98:99] offset:256
	s_add_u32 s98, s98, 0x8000
	s_addc_u32 s99, s99, 0
	global_load_dwordx4 v[244:247], v144, s[98:99]
	global_load_dwordx4 v[248:251], v144, s[98:99] offset:256
	s_mov_b64 s[28:29], exec
	s_mov_b64 s[98:99], s[10:11]
	ds_write_b128 v140, v[124:127]
	ds_write_b128 v141, v[120:123]
	ds_write_b128 v140, v[116:119] offset:128
	ds_write_b128 v141, v[112:115] offset:128
	s_waitcnt lgkmcnt(0)
	ds_read_b128 v[146:149], v142
	ds_read_b128 v[150:153], v143
	ds_read_b128 v[154:157], v142 offset:128
	ds_read_b128 v[158:161], v143 offset:128
	s_waitcnt vmcnt(14)
	s_waitcnt lgkmcnt(0)
	v_lshlrev_b32_e32 v162, 16, v188
	v_and_b32_e32 v163, 0xffff0000, v188
	v_lshlrev_b32_e32 v164, 16, v189
	v_and_b32_e32 v165, 0xffff0000, v189
	v_lshlrev_b32_e32 v166, 16, v190
	v_and_b32_e32 v167, 0xffff0000, v190
	v_lshlrev_b32_e32 v168, 16, v191
	v_and_b32_e32 v169, 0xffff0000, v191
	v_pk_add_f32 v[146:147], v[146:147], v[162:163]
	v_pk_add_f32 v[148:149], v[148:149], v[164:165]
	v_pk_add_f32 v[150:151], v[150:151], v[166:167]
	v_pk_add_f32 v[152:153], v[152:153], v[168:169]
	v_pk_mul_f32 v[170:171], v[146:147], v[146:147]
	v_pk_fma_f32 v[170:171], v[148:149], v[148:149], v[170:171]
	v_pk_fma_f32 v[170:171], v[150:151], v[150:151], v[170:171]
	v_pk_fma_f32 v[170:171], v[152:153], v[152:153], v[170:171]
	v_cvt_pk_bf16_f32 v172, v146, v147
	v_cvt_pk_bf16_f32 v173, v148, v149
	v_cvt_pk_bf16_f32 v174, v150, v151
	v_cvt_pk_bf16_f32 v175, v152, v153
	global_store_dwordx4 v144, v[172:175], s[98:99]
	v_lshlrev_b32_e32 v162, 16, v192
	v_and_b32_e32 v163, 0xffff0000, v192
	v_lshlrev_b32_e32 v164, 16, v193
	v_and_b32_e32 v165, 0xffff0000, v193
	v_lshlrev_b32_e32 v166, 16, v194
	v_and_b32_e32 v167, 0xffff0000, v194
	v_lshlrev_b32_e32 v168, 16, v195
	v_and_b32_e32 v169, 0xffff0000, v195
	v_pk_add_f32 v[154:155], v[154:155], v[162:163]
	v_pk_add_f32 v[156:157], v[156:157], v[164:165]
	v_pk_add_f32 v[158:159], v[158:159], v[166:167]
	v_pk_add_f32 v[160:161], v[160:161], v[168:169]
	v_pk_fma_f32 v[170:171], v[154:155], v[154:155], v[170:171]
	v_pk_fma_f32 v[170:171], v[156:157], v[156:157], v[170:171]
	v_pk_fma_f32 v[170:171], v[158:159], v[158:159], v[170:171]
	v_pk_fma_f32 v[170:171], v[160:161], v[160:161], v[170:171]
	v_cvt_pk_bf16_f32 v176, v154, v155
	v_cvt_pk_bf16_f32 v177, v156, v157
	v_cvt_pk_bf16_f32 v178, v158, v159
	v_cvt_pk_bf16_f32 v179, v160, v161
	global_store_dwordx4 v144, v[176:179], s[98:99] offset:256
	v_add_f32_e32 v162, v170, v171
	s_nop 1
	v_add_f32_dpp v163, v162, v162 quad_perm:[1,0,3,2] row_mask:0xf bank_mask:0xf
	s_nop 1
	v_add_f32_dpp v164, v163, v163 quad_perm:[2,3,0,1] row_mask:0xf bank_mask:0xf
	s_mov_b64 exec, vcc
	global_atomic_add_f32 v145, v164, s[12:13] offset:0
	s_mov_b64 exec, s[28:29]
	s_add_u32 s98, s98, 0x8000
	s_addc_u32 s99, s99, 0
	ds_write_b128 v140, v[108:111]
	ds_write_b128 v141, v[104:107]
	ds_write_b128 v140, v[100:103] offset:128
	ds_write_b128 v141, v[96:99] offset:128
	s_waitcnt lgkmcnt(0)
	ds_read_b128 v[146:149], v142
	ds_read_b128 v[150:153], v143
	ds_read_b128 v[154:157], v142 offset:128
	ds_read_b128 v[158:161], v143 offset:128
	s_waitcnt vmcnt(15)
	s_waitcnt lgkmcnt(0)
	v_lshlrev_b32_e32 v162, 16, v196
	v_and_b32_e32 v163, 0xffff0000, v196
	v_lshlrev_b32_e32 v164, 16, v197
	v_and_b32_e32 v165, 0xffff0000, v197
	v_lshlrev_b32_e32 v166, 16, v198
	v_and_b32_e32 v167, 0xffff0000, v198
	v_lshlrev_b32_e32 v168, 16, v199
	v_and_b32_e32 v169, 0xffff0000, v199
	v_pk_add_f32 v[146:147], v[146:147], v[162:163]
	v_pk_add_f32 v[148:149], v[148:149], v[164:165]
	v_pk_add_f32 v[150:151], v[150:151], v[166:167]
	v_pk_add_f32 v[152:153], v[152:153], v[168:169]
	v_pk_mul_f32 v[170:171], v[146:147], v[146:147]
	v_pk_fma_f32 v[170:171], v[148:149], v[148:149], v[170:171]
	v_pk_fma_f32 v[170:171], v[150:151], v[150:151], v[170:171]
	v_pk_fma_f32 v[170:171], v[152:153], v[152:153], v[170:171]
	v_cvt_pk_bf16_f32 v172, v146, v147
	v_cvt_pk_bf16_f32 v173, v148, v149
	v_cvt_pk_bf16_f32 v174, v150, v151
	v_cvt_pk_bf16_f32 v175, v152, v153
	global_store_dwordx4 v144, v[172:175], s[98:99]
	v_lshlrev_b32_e32 v162, 16, v200
	v_and_b32_e32 v163, 0xffff0000, v200
	v_lshlrev_b32_e32 v164, 16, v201
	v_and_b32_e32 v165, 0xffff0000, v201
	v_lshlrev_b32_e32 v166, 16, v202
	v_and_b32_e32 v167, 0xffff0000, v202
	v_lshlrev_b32_e32 v168, 16, v203
	v_and_b32_e32 v169, 0xffff0000, v203
	v_pk_add_f32 v[154:155], v[154:155], v[162:163]
	v_pk_add_f32 v[156:157], v[156:157], v[164:165]
	v_pk_add_f32 v[158:159], v[158:159], v[166:167]
	v_pk_add_f32 v[160:161], v[160:161], v[168:169]
	v_pk_fma_f32 v[170:171], v[154:155], v[154:155], v[170:171]
	v_pk_fma_f32 v[170:171], v[156:157], v[156:157], v[170:171]
	v_pk_fma_f32 v[170:171], v[158:159], v[158:159], v[170:171]
	v_pk_fma_f32 v[170:171], v[160:161], v[160:161], v[170:171]
	v_cvt_pk_bf16_f32 v176, v154, v155
	v_cvt_pk_bf16_f32 v177, v156, v157
	v_cvt_pk_bf16_f32 v178, v158, v159
	v_cvt_pk_bf16_f32 v179, v160, v161
	global_store_dwordx4 v144, v[176:179], s[98:99] offset:256
	v_add_f32_e32 v162, v170, v171
	s_nop 1
	v_add_f32_dpp v163, v162, v162 quad_perm:[1,0,3,2] row_mask:0xf bank_mask:0xf
	s_nop 1
	v_add_f32_dpp v164, v163, v163 quad_perm:[2,3,0,1] row_mask:0xf bank_mask:0xf
	s_mov_b64 exec, vcc
	global_atomic_add_f32 v145, v164, s[12:13] offset:64
	s_mov_b64 exec, s[28:29]
	s_add_u32 s98, s98, 0x8000
	s_addc_u32 s99, s99, 0
	ds_write_b128 v140, v[92:95]
	ds_write_b128 v141, v[88:91]
	ds_write_b128 v140, v[84:87] offset:128
	ds_write_b128 v141, v[80:83] offset:128
	s_waitcnt lgkmcnt(0)
	ds_read_b128 v[146:149], v142
	ds_read_b128 v[150:153], v143
	ds_read_b128 v[154:157], v142 offset:128
	ds_read_b128 v[158:161], v143 offset:128
	s_waitcnt vmcnt(16)
	s_waitcnt lgkmcnt(0)
	v_lshlrev_b32_e32 v162, 16, v204
	v_and_b32_e32 v163, 0xffff0000, v204
	v_lshlrev_b32_e32 v164, 16, v205
	v_and_b32_e32 v165, 0xffff0000, v205
	v_lshlrev_b32_e32 v166, 16, v206
	v_and_b32_e32 v167, 0xffff0000, v206
	v_lshlrev_b32_e32 v168, 16, v207
	v_and_b32_e32 v169, 0xffff0000, v207
	v_pk_add_f32 v[146:147], v[146:147], v[162:163]
	v_pk_add_f32 v[148:149], v[148:149], v[164:165]
	v_pk_add_f32 v[150:151], v[150:151], v[166:167]
	v_pk_add_f32 v[152:153], v[152:153], v[168:169]
	v_pk_mul_f32 v[170:171], v[146:147], v[146:147]
	v_pk_fma_f32 v[170:171], v[148:149], v[148:149], v[170:171]
	v_pk_fma_f32 v[170:171], v[150:151], v[150:151], v[170:171]
	v_pk_fma_f32 v[170:171], v[152:153], v[152:153], v[170:171]
	v_cvt_pk_bf16_f32 v172, v146, v147
	v_cvt_pk_bf16_f32 v173, v148, v149
	v_cvt_pk_bf16_f32 v174, v150, v151
	v_cvt_pk_bf16_f32 v175, v152, v153
	global_store_dwordx4 v144, v[172:175], s[98:99]
	v_lshlrev_b32_e32 v162, 16, v208
	v_and_b32_e32 v163, 0xffff0000, v208
	v_lshlrev_b32_e32 v164, 16, v209
	v_and_b32_e32 v165, 0xffff0000, v209
	v_lshlrev_b32_e32 v166, 16, v210
	v_and_b32_e32 v167, 0xffff0000, v210
	v_lshlrev_b32_e32 v168, 16, v211
	v_and_b32_e32 v169, 0xffff0000, v211
	v_pk_add_f32 v[154:155], v[154:155], v[162:163]
	v_pk_add_f32 v[156:157], v[156:157], v[164:165]
	v_pk_add_f32 v[158:159], v[158:159], v[166:167]
	v_pk_add_f32 v[160:161], v[160:161], v[168:169]
	v_pk_fma_f32 v[170:171], v[154:155], v[154:155], v[170:171]
	v_pk_fma_f32 v[170:171], v[156:157], v[156:157], v[170:171]
	v_pk_fma_f32 v[170:171], v[158:159], v[158:159], v[170:171]
	v_pk_fma_f32 v[170:171], v[160:161], v[160:161], v[170:171]
	v_cvt_pk_bf16_f32 v176, v154, v155
	v_cvt_pk_bf16_f32 v177, v156, v157
	v_cvt_pk_bf16_f32 v178, v158, v159
	v_cvt_pk_bf16_f32 v179, v160, v161
	global_store_dwordx4 v144, v[176:179], s[98:99] offset:256
	v_add_f32_e32 v162, v170, v171
	s_nop 1
	v_add_f32_dpp v163, v162, v162 quad_perm:[1,0,3,2] row_mask:0xf bank_mask:0xf
	s_nop 1
	v_add_f32_dpp v164, v163, v163 quad_perm:[2,3,0,1] row_mask:0xf bank_mask:0xf
	s_mov_b64 exec, vcc
	global_atomic_add_f32 v145, v164, s[12:13] offset:128
	s_mov_b64 exec, s[28:29]
	s_add_u32 s98, s98, 0x8000
	s_addc_u32 s99, s99, 0
	ds_write_b128 v140, v[76:79]
	ds_write_b128 v141, v[72:75]
	ds_write_b128 v140, v[68:71] offset:128
	ds_write_b128 v141, v[64:67] offset:128
	s_waitcnt lgkmcnt(0)
	ds_read_b128 v[146:149], v142
	ds_read_b128 v[150:153], v143
	ds_read_b128 v[154:157], v142 offset:128
	ds_read_b128 v[158:161], v143 offset:128
	s_waitcnt vmcnt(17)
	s_waitcnt lgkmcnt(0)
	v_lshlrev_b32_e32 v162, 16, v212
	v_and_b32_e32 v163, 0xffff0000, v212
	v_lshlrev_b32_e32 v164, 16, v213
	v_and_b32_e32 v165, 0xffff0000, v213
	v_lshlrev_b32_e32 v166, 16, v214
	v_and_b32_e32 v167, 0xffff0000, v214
	v_lshlrev_b32_e32 v168, 16, v215
	v_and_b32_e32 v169, 0xffff0000, v215
	v_pk_add_f32 v[146:147], v[146:147], v[162:163]
	v_pk_add_f32 v[148:149], v[148:149], v[164:165]
	v_pk_add_f32 v[150:151], v[150:151], v[166:167]
	v_pk_add_f32 v[152:153], v[152:153], v[168:169]
	v_pk_mul_f32 v[170:171], v[146:147], v[146:147]
	v_pk_fma_f32 v[170:171], v[148:149], v[148:149], v[170:171]
	v_pk_fma_f32 v[170:171], v[150:151], v[150:151], v[170:171]
	v_pk_fma_f32 v[170:171], v[152:153], v[152:153], v[170:171]
	v_cvt_pk_bf16_f32 v172, v146, v147
	v_cvt_pk_bf16_f32 v173, v148, v149
	v_cvt_pk_bf16_f32 v174, v150, v151
	v_cvt_pk_bf16_f32 v175, v152, v153
	global_store_dwordx4 v144, v[172:175], s[98:99]
	v_lshlrev_b32_e32 v162, 16, v216
	v_and_b32_e32 v163, 0xffff0000, v216
	v_lshlrev_b32_e32 v164, 16, v217
	v_and_b32_e32 v165, 0xffff0000, v217
	v_lshlrev_b32_e32 v166, 16, v218
	v_and_b32_e32 v167, 0xffff0000, v218
	v_lshlrev_b32_e32 v168, 16, v219
	v_and_b32_e32 v169, 0xffff0000, v219
	v_pk_add_f32 v[154:155], v[154:155], v[162:163]
	v_pk_add_f32 v[156:157], v[156:157], v[164:165]
	v_pk_add_f32 v[158:159], v[158:159], v[166:167]
	v_pk_add_f32 v[160:161], v[160:161], v[168:169]
	v_pk_fma_f32 v[170:171], v[154:155], v[154:155], v[170:171]
	v_pk_fma_f32 v[170:171], v[156:157], v[156:157], v[170:171]
	v_pk_fma_f32 v[170:171], v[158:159], v[158:159], v[170:171]
	v_pk_fma_f32 v[170:171], v[160:161], v[160:161], v[170:171]
	v_cvt_pk_bf16_f32 v176, v154, v155
	v_cvt_pk_bf16_f32 v177, v156, v157
	v_cvt_pk_bf16_f32 v178, v158, v159
	v_cvt_pk_bf16_f32 v179, v160, v161
	global_store_dwordx4 v144, v[176:179], s[98:99] offset:256
	v_add_f32_e32 v162, v170, v171
	s_nop 1
	v_add_f32_dpp v163, v162, v162 quad_perm:[1,0,3,2] row_mask:0xf bank_mask:0xf
	s_nop 1
	v_add_f32_dpp v164, v163, v163 quad_perm:[2,3,0,1] row_mask:0xf bank_mask:0xf
	s_mov_b64 exec, vcc
	global_atomic_add_f32 v145, v164, s[12:13] offset:192
	s_mov_b64 exec, s[28:29]
	s_add_u32 s98, s98, 0x28000
	s_addc_u32 s99, s99, 0
	ds_write_b128 v140, v[60:63]
	ds_write_b128 v141, v[56:59]
	ds_write_b128 v140, v[52:55] offset:128
	ds_write_b128 v141, v[48:51] offset:128
	s_waitcnt lgkmcnt(0)
	ds_read_b128 v[146:149], v142
	ds_read_b128 v[150:153], v143
	ds_read_b128 v[154:157], v142 offset:128
	ds_read_b128 v[158:161], v143 offset:128
	s_waitcnt vmcnt(18)
	s_waitcnt lgkmcnt(0)
	v_lshlrev_b32_e32 v162, 16, v220
	v_and_b32_e32 v163, 0xffff0000, v220
	v_lshlrev_b32_e32 v164, 16, v221
	v_and_b32_e32 v165, 0xffff0000, v221
	v_lshlrev_b32_e32 v166, 16, v222
	v_and_b32_e32 v167, 0xffff0000, v222
	v_lshlrev_b32_e32 v168, 16, v223
	v_and_b32_e32 v169, 0xffff0000, v223
	v_pk_add_f32 v[146:147], v[146:147], v[162:163]
	v_pk_add_f32 v[148:149], v[148:149], v[164:165]
	v_pk_add_f32 v[150:151], v[150:151], v[166:167]
	v_pk_add_f32 v[152:153], v[152:153], v[168:169]
	v_pk_mul_f32 v[170:171], v[146:147], v[146:147]
	v_pk_fma_f32 v[170:171], v[148:149], v[148:149], v[170:171]
	v_pk_fma_f32 v[170:171], v[150:151], v[150:151], v[170:171]
	v_pk_fma_f32 v[170:171], v[152:153], v[152:153], v[170:171]
	v_cvt_pk_bf16_f32 v172, v146, v147
	v_cvt_pk_bf16_f32 v173, v148, v149
	v_cvt_pk_bf16_f32 v174, v150, v151
	v_cvt_pk_bf16_f32 v175, v152, v153
	global_store_dwordx4 v144, v[172:175], s[98:99]
	v_lshlrev_b32_e32 v162, 16, v224
	v_and_b32_e32 v163, 0xffff0000, v224
	v_lshlrev_b32_e32 v164, 16, v225
	v_and_b32_e32 v165, 0xffff0000, v225
	v_lshlrev_b32_e32 v166, 16, v226
	v_and_b32_e32 v167, 0xffff0000, v226
	v_lshlrev_b32_e32 v168, 16, v227
	v_and_b32_e32 v169, 0xffff0000, v227
	v_pk_add_f32 v[154:155], v[154:155], v[162:163]
	v_pk_add_f32 v[156:157], v[156:157], v[164:165]
	v_pk_add_f32 v[158:159], v[158:159], v[166:167]
	v_pk_add_f32 v[160:161], v[160:161], v[168:169]
	v_pk_fma_f32 v[170:171], v[154:155], v[154:155], v[170:171]
	v_pk_fma_f32 v[170:171], v[156:157], v[156:157], v[170:171]
	v_pk_fma_f32 v[170:171], v[158:159], v[158:159], v[170:171]
	v_pk_fma_f32 v[170:171], v[160:161], v[160:161], v[170:171]
	v_cvt_pk_bf16_f32 v176, v154, v155
	v_cvt_pk_bf16_f32 v177, v156, v157
	v_cvt_pk_bf16_f32 v178, v158, v159
	v_cvt_pk_bf16_f32 v179, v160, v161
	global_store_dwordx4 v144, v[176:179], s[98:99] offset:256
	v_add_f32_e32 v162, v170, v171
	s_nop 1
	v_add_f32_dpp v163, v162, v162 quad_perm:[1,0,3,2] row_mask:0xf bank_mask:0xf
	s_nop 1
	v_add_f32_dpp v164, v163, v163 quad_perm:[2,3,0,1] row_mask:0xf bank_mask:0xf
	s_mov_b64 exec, vcc
	global_atomic_add_f32 v145, v164, s[12:13] offset:512
	s_mov_b64 exec, s[28:29]
	s_add_u32 s98, s98, 0x8000
	s_addc_u32 s99, s99, 0
	ds_write_b128 v140, v[44:47]
	ds_write_b128 v141, v[40:43]
	ds_write_b128 v140, v[36:39] offset:128
	ds_write_b128 v141, v[32:35] offset:128
	s_waitcnt lgkmcnt(0)
	ds_read_b128 v[146:149], v142
	ds_read_b128 v[150:153], v143
	ds_read_b128 v[154:157], v142 offset:128
	ds_read_b128 v[158:161], v143 offset:128
	s_waitcnt vmcnt(19)
	s_waitcnt lgkmcnt(0)
	v_lshlrev_b32_e32 v162, 16, v228
	v_and_b32_e32 v163, 0xffff0000, v228
	v_lshlrev_b32_e32 v164, 16, v229
	v_and_b32_e32 v165, 0xffff0000, v229
	v_lshlrev_b32_e32 v166, 16, v230
	v_and_b32_e32 v167, 0xffff0000, v230
	v_lshlrev_b32_e32 v168, 16, v231
	v_and_b32_e32 v169, 0xffff0000, v231
	v_pk_add_f32 v[146:147], v[146:147], v[162:163]
	v_pk_add_f32 v[148:149], v[148:149], v[164:165]
	v_pk_add_f32 v[150:151], v[150:151], v[166:167]
	v_pk_add_f32 v[152:153], v[152:153], v[168:169]
	v_pk_mul_f32 v[170:171], v[146:147], v[146:147]
	v_pk_fma_f32 v[170:171], v[148:149], v[148:149], v[170:171]
	v_pk_fma_f32 v[170:171], v[150:151], v[150:151], v[170:171]
	v_pk_fma_f32 v[170:171], v[152:153], v[152:153], v[170:171]
	v_cvt_pk_bf16_f32 v172, v146, v147
	v_cvt_pk_bf16_f32 v173, v148, v149
	v_cvt_pk_bf16_f32 v174, v150, v151
	v_cvt_pk_bf16_f32 v175, v152, v153
	global_store_dwordx4 v144, v[172:175], s[98:99]
	v_lshlrev_b32_e32 v162, 16, v232
	v_and_b32_e32 v163, 0xffff0000, v232
	v_lshlrev_b32_e32 v164, 16, v233
	v_and_b32_e32 v165, 0xffff0000, v233
	v_lshlrev_b32_e32 v166, 16, v234
	v_and_b32_e32 v167, 0xffff0000, v234
	v_lshlrev_b32_e32 v168, 16, v235
	v_and_b32_e32 v169, 0xffff0000, v235
	v_pk_add_f32 v[154:155], v[154:155], v[162:163]
	v_pk_add_f32 v[156:157], v[156:157], v[164:165]
	v_pk_add_f32 v[158:159], v[158:159], v[166:167]
	v_pk_add_f32 v[160:161], v[160:161], v[168:169]
	v_pk_fma_f32 v[170:171], v[154:155], v[154:155], v[170:171]
	v_pk_fma_f32 v[170:171], v[156:157], v[156:157], v[170:171]
	v_pk_fma_f32 v[170:171], v[158:159], v[158:159], v[170:171]
	v_pk_fma_f32 v[170:171], v[160:161], v[160:161], v[170:171]
	v_cvt_pk_bf16_f32 v176, v154, v155
	v_cvt_pk_bf16_f32 v177, v156, v157
	v_cvt_pk_bf16_f32 v178, v158, v159
	v_cvt_pk_bf16_f32 v179, v160, v161
	global_store_dwordx4 v144, v[176:179], s[98:99] offset:256
	v_add_f32_e32 v162, v170, v171
	s_nop 1
	v_add_f32_dpp v163, v162, v162 quad_perm:[1,0,3,2] row_mask:0xf bank_mask:0xf
	s_nop 1
	v_add_f32_dpp v164, v163, v163 quad_perm:[2,3,0,1] row_mask:0xf bank_mask:0xf
	s_mov_b64 exec, vcc
	global_atomic_add_f32 v145, v164, s[12:13] offset:576
	s_mov_b64 exec, s[28:29]
	s_add_u32 s98, s98, 0x8000
	s_addc_u32 s99, s99, 0
	ds_write_b128 v140, v[28:31]
	ds_write_b128 v141, v[24:27]
	ds_write_b128 v140, v[20:23] offset:128
	ds_write_b128 v141, v[16:19] offset:128
	s_waitcnt lgkmcnt(0)
	ds_read_b128 v[146:149], v142
	ds_read_b128 v[150:153], v143
	ds_read_b128 v[154:157], v142 offset:128
	ds_read_b128 v[158:161], v143 offset:128
	s_waitcnt vmcnt(20)
	s_waitcnt lgkmcnt(0)
	v_lshlrev_b32_e32 v162, 16, v236
	v_and_b32_e32 v163, 0xffff0000, v236
	v_lshlrev_b32_e32 v164, 16, v237
	v_and_b32_e32 v165, 0xffff0000, v237
	v_lshlrev_b32_e32 v166, 16, v238
	v_and_b32_e32 v167, 0xffff0000, v238
	v_lshlrev_b32_e32 v168, 16, v239
	v_and_b32_e32 v169, 0xffff0000, v239
	v_pk_add_f32 v[146:147], v[146:147], v[162:163]
	v_pk_add_f32 v[148:149], v[148:149], v[164:165]
	v_pk_add_f32 v[150:151], v[150:151], v[166:167]
	v_pk_add_f32 v[152:153], v[152:153], v[168:169]
	v_pk_mul_f32 v[170:171], v[146:147], v[146:147]
	v_pk_fma_f32 v[170:171], v[148:149], v[148:149], v[170:171]
	v_pk_fma_f32 v[170:171], v[150:151], v[150:151], v[170:171]
	v_pk_fma_f32 v[170:171], v[152:153], v[152:153], v[170:171]
	v_cvt_pk_bf16_f32 v172, v146, v147
	v_cvt_pk_bf16_f32 v173, v148, v149
	v_cvt_pk_bf16_f32 v174, v150, v151
	v_cvt_pk_bf16_f32 v175, v152, v153
	global_store_dwordx4 v144, v[172:175], s[98:99]
	v_lshlrev_b32_e32 v162, 16, v240
	v_and_b32_e32 v163, 0xffff0000, v240
	v_lshlrev_b32_e32 v164, 16, v241
	v_and_b32_e32 v165, 0xffff0000, v241
	v_lshlrev_b32_e32 v166, 16, v242
	v_and_b32_e32 v167, 0xffff0000, v242
	v_lshlrev_b32_e32 v168, 16, v243
	v_and_b32_e32 v169, 0xffff0000, v243
	v_pk_add_f32 v[154:155], v[154:155], v[162:163]
	v_pk_add_f32 v[156:157], v[156:157], v[164:165]
	v_pk_add_f32 v[158:159], v[158:159], v[166:167]
	v_pk_add_f32 v[160:161], v[160:161], v[168:169]
	v_pk_fma_f32 v[170:171], v[154:155], v[154:155], v[170:171]
	v_pk_fma_f32 v[170:171], v[156:157], v[156:157], v[170:171]
	v_pk_fma_f32 v[170:171], v[158:159], v[158:159], v[170:171]
	v_pk_fma_f32 v[170:171], v[160:161], v[160:161], v[170:171]
	v_cvt_pk_bf16_f32 v176, v154, v155
	v_cvt_pk_bf16_f32 v177, v156, v157
	v_cvt_pk_bf16_f32 v178, v158, v159
	v_cvt_pk_bf16_f32 v179, v160, v161
	global_store_dwordx4 v144, v[176:179], s[98:99] offset:256
	v_add_f32_e32 v162, v170, v171
	s_nop 1
	v_add_f32_dpp v163, v162, v162 quad_perm:[1,0,3,2] row_mask:0xf bank_mask:0xf
	s_nop 1
	v_add_f32_dpp v164, v163, v163 quad_perm:[2,3,0,1] row_mask:0xf bank_mask:0xf
	s_mov_b64 exec, vcc
	global_atomic_add_f32 v145, v164, s[12:13] offset:640
	s_mov_b64 exec, s[28:29]
	s_add_u32 s98, s98, 0x8000
	s_addc_u32 s99, s99, 0
	ds_write_b128 v140, v[12:15]
	ds_write_b128 v141, v[8:11]
	ds_write_b128 v140, v[4:7] offset:128
	ds_write_b128 v141, v[0:3] offset:128
	s_waitcnt lgkmcnt(0)
	ds_read_b128 v[146:149], v142
	ds_read_b128 v[150:153], v143
	ds_read_b128 v[154:157], v142 offset:128
	ds_read_b128 v[158:161], v143 offset:128
	s_waitcnt vmcnt(21)
	s_waitcnt lgkmcnt(0)
	v_lshlrev_b32_e32 v162, 16, v244
	v_and_b32_e32 v163, 0xffff0000, v244
	v_lshlrev_b32_e32 v164, 16, v245
	v_and_b32_e32 v165, 0xffff0000, v245
	v_lshlrev_b32_e32 v166, 16, v246
	v_and_b32_e32 v167, 0xffff0000, v246
	v_lshlrev_b32_e32 v168, 16, v247
	v_and_b32_e32 v169, 0xffff0000, v247
	v_pk_add_f32 v[146:147], v[146:147], v[162:163]
	v_pk_add_f32 v[148:149], v[148:149], v[164:165]
	v_pk_add_f32 v[150:151], v[150:151], v[166:167]
	v_pk_add_f32 v[152:153], v[152:153], v[168:169]
	v_pk_mul_f32 v[170:171], v[146:147], v[146:147]
	v_pk_fma_f32 v[170:171], v[148:149], v[148:149], v[170:171]
	v_pk_fma_f32 v[170:171], v[150:151], v[150:151], v[170:171]
	v_pk_fma_f32 v[170:171], v[152:153], v[152:153], v[170:171]
	v_cvt_pk_bf16_f32 v172, v146, v147
	v_cvt_pk_bf16_f32 v173, v148, v149
	v_cvt_pk_bf16_f32 v174, v150, v151
	v_cvt_pk_bf16_f32 v175, v152, v153
	global_store_dwordx4 v144, v[172:175], s[98:99]
	v_lshlrev_b32_e32 v162, 16, v248
	v_and_b32_e32 v163, 0xffff0000, v248
	v_lshlrev_b32_e32 v164, 16, v249
	v_and_b32_e32 v165, 0xffff0000, v249
	v_lshlrev_b32_e32 v166, 16, v250
	v_and_b32_e32 v167, 0xffff0000, v250
	v_lshlrev_b32_e32 v168, 16, v251
	v_and_b32_e32 v169, 0xffff0000, v251
	v_pk_add_f32 v[154:155], v[154:155], v[162:163]
	v_pk_add_f32 v[156:157], v[156:157], v[164:165]
	v_pk_add_f32 v[158:159], v[158:159], v[166:167]
	v_pk_add_f32 v[160:161], v[160:161], v[168:169]
	v_pk_fma_f32 v[170:171], v[154:155], v[154:155], v[170:171]
	v_pk_fma_f32 v[170:171], v[156:157], v[156:157], v[170:171]
	v_pk_fma_f32 v[170:171], v[158:159], v[158:159], v[170:171]
	v_pk_fma_f32 v[170:171], v[160:161], v[160:161], v[170:171]
	v_cvt_pk_bf16_f32 v176, v154, v155
	v_cvt_pk_bf16_f32 v177, v156, v157
	v_cvt_pk_bf16_f32 v178, v158, v159
	v_cvt_pk_bf16_f32 v179, v160, v161
	global_store_dwordx4 v144, v[176:179], s[98:99] offset:256
	v_add_f32_e32 v162, v170, v171
	s_nop 1
	v_add_f32_dpp v163, v162, v162 quad_perm:[1,0,3,2] row_mask:0xf bank_mask:0xf
	s_nop 1
	v_add_f32_dpp v164, v163, v163 quad_perm:[2,3,0,1] row_mask:0xf bank_mask:0xf
	s_mov_b64 exec, vcc
	global_atomic_add_f32 v145, v164, s[12:13] offset:704
	s_mov_b64 exec, s[28:29]

.LBB0_1920:
	v_and_b32_e32 v146, 63, v180
	v_and_b32_e32 v147, 15, v180
	v_bfe_u32 v148, v180, 4, 2
	v_lshrrev_b32_e32 v149, 6, v180
	v_lshlrev_b32_e32 v149, 12, v149
	v_add_u32_e32 v149, 0x20000, v149
	v_and_b32_e32 v150, 7, v147
	v_xor_b32_e32 v150, v148, v150
	v_lshlrev_b32_e32 v150, 4, v150
	v_lshl_add_u32 v150, v147, 8, v150
	v_add_u32_e32 v140, v149, v150
	v_xor_b32_e32 v141, 64, v140
	v_lshrrev_b32_e32 v151, 2, v146
	v_and_b32_e32 v152, 3, v146
	v_and_b32_e32 v153, 7, v151
	v_lshlrev_b32_e32 v154, 1, v152
	v_xor_b32_e32 v154, v154, v153
	v_lshlrev_b32_e32 v154, 4, v154
	v_lshl_add_u32 v154, v151, 8, v154
	v_add_u32_e32 v142, v149, v154
	v_xor_b32_e32 v143, 16, v142
	s_lshl_b32 s18, s48, 8
	s_add_i32 s18, s18, s37
	v_add_u32_e32 v155, s18, v151
	v_lshlrev_b32_e32 v145, 2, v155
	v_lshlrev_b32_e32 v155, 11, v155
	s_lshl_b32 s18, s45, 8
	s_add_i32 s18, s18, s38
	v_lshl_add_u32 v156, v152, 3, s18
	v_lshl_add_u32 v144, v156, 1, v155
	v_cmp_eq_u32_e32 vcc, 0, v152
	s_mov_b64 s[98:99], s[8:9]
	global_load_dwordx4 v[188:191], v144, s[98:99]
	global_load_dwordx4 v[192:195], v144, s[98:99] offset:256
	s_add_u32 s98, s98, 0x8000
	s_addc_u32 s99, s99, 0
	global_load_dwordx4 v[196:199], v144, s[98:99]
	global_load_dwordx4 v[200:203], v144, s[98:99] offset:256
	s_add_u32 s98, s98, 0x8000
	s_addc_u32 s99, s99, 0
	global_load_dwordx4 v[204:207], v144, s[98:99]
	global_load_dwordx4 v[208:211], v144, s[98:99] offset:256
	s_add_u32 s98, s98, 0x8000
	s_addc_u32 s99, s99, 0
	global_load_dwordx4 v[212:215], v144, s[98:99]
	global_load_dwordx4 v[216:219], v144, s[98:99] offset:256
	s_add_u32 s98, s98, 0x28000
	s_addc_u32 s99, s99, 0
	global_load_dwordx4 v[220:223], v144, s[98:99]
	global_load_dwordx4 v[224:227], v144, s[98:99] offset:256
	s_add_u32 s98, s98, 0x8000
	s_addc_u32 s99, s99, 0
	global_load_dwordx4 v[228:231], v144, s[98:99]
	global_load_dwordx4 v[232:235], v144, s[98:99] offset:256
	s_add_u32 s98, s98, 0x8000
	s_addc_u32 s99, s99, 0
	global_load_dwordx4 v[236:239], v144, s[98:99]
	global_load_dwordx4 v[240:243], v144, s[98:99] offset:256
	s_add_u32 s98, s98, 0x8000
	s_addc_u32 s99, s99, 0
	global_load_dwordx4 v[244:247], v144, s[98:99]
	global_load_dwordx4 v[248:251], v144, s[98:99] offset:256
	s_mov_b64 s[18:19], exec
	s_mov_b64 s[98:99], s[8:9]
	ds_write_b128 v140, v[124:127]
	ds_write_b128 v141, v[120:123]
	ds_write_b128 v140, v[116:119] offset:128
	ds_write_b128 v141, v[112:115] offset:128
	s_waitcnt lgkmcnt(0)
	ds_read_b128 v[146:149], v142
	ds_read_b128 v[150:153], v143
	ds_read_b128 v[154:157], v142 offset:128
	ds_read_b128 v[158:161], v143 offset:128
	s_waitcnt vmcnt(14)
	s_waitcnt lgkmcnt(0)
	v_lshlrev_b32_e32 v162, 16, v188
	v_and_b32_e32 v163, 0xffff0000, v188
	v_lshlrev_b32_e32 v164, 16, v189
	v_and_b32_e32 v165, 0xffff0000, v189
	v_lshlrev_b32_e32 v166, 16, v190
	v_and_b32_e32 v167, 0xffff0000, v190
	v_lshlrev_b32_e32 v168, 16, v191
	v_and_b32_e32 v169, 0xffff0000, v191
	v_pk_add_f32 v[146:147], v[146:147], v[162:163]
	v_pk_add_f32 v[148:149], v[148:149], v[164:165]
	v_pk_add_f32 v[150:151], v[150:151], v[166:167]
	v_pk_add_f32 v[152:153], v[152:153], v[168:169]
	v_pk_mul_f32 v[170:171], v[146:147], v[146:147]
	v_pk_fma_f32 v[170:171], v[148:149], v[148:149], v[170:171]
	v_pk_fma_f32 v[170:171], v[150:151], v[150:151], v[170:171]
	v_pk_fma_f32 v[170:171], v[152:153], v[152:153], v[170:171]
	v_cvt_pk_bf16_f32 v172, v146, v147
	v_cvt_pk_bf16_f32 v173, v148, v149
	v_cvt_pk_bf16_f32 v174, v150, v151
	v_cvt_pk_bf16_f32 v175, v152, v153
	global_store_dwordx4 v144, v[172:175], s[98:99]
	v_lshlrev_b32_e32 v162, 16, v192
	v_and_b32_e32 v163, 0xffff0000, v192
	v_lshlrev_b32_e32 v164, 16, v193
	v_and_b32_e32 v165, 0xffff0000, v193
	v_lshlrev_b32_e32 v166, 16, v194
	v_and_b32_e32 v167, 0xffff0000, v194
	v_lshlrev_b32_e32 v168, 16, v195
	v_and_b32_e32 v169, 0xffff0000, v195
	v_pk_add_f32 v[154:155], v[154:155], v[162:163]
	v_pk_add_f32 v[156:157], v[156:157], v[164:165]
	v_pk_add_f32 v[158:159], v[158:159], v[166:167]
	v_pk_add_f32 v[160:161], v[160:161], v[168:169]
	v_pk_fma_f32 v[170:171], v[154:155], v[154:155], v[170:171]
	v_pk_fma_f32 v[170:171], v[156:157], v[156:157], v[170:171]
	v_pk_fma_f32 v[170:171], v[158:159], v[158:159], v[170:171]
	v_pk_fma_f32 v[170:171], v[160:161], v[160:161], v[170:171]
	v_cvt_pk_bf16_f32 v176, v154, v155
	v_cvt_pk_bf16_f32 v177, v156, v157
	v_cvt_pk_bf16_f32 v178, v158, v159
	v_cvt_pk_bf16_f32 v179, v160, v161
	global_store_dwordx4 v144, v[176:179], s[98:99] offset:256
	v_add_f32_e32 v162, v170, v171
	s_nop 1
	v_add_f32_dpp v163, v162, v162 quad_perm:[1,0,3,2] row_mask:0xf bank_mask:0xf
	s_nop 1
	v_add_f32_dpp v164, v163, v163 quad_perm:[2,3,0,1] row_mask:0xf bank_mask:0xf
	s_mov_b64 exec, vcc
	global_atomic_add_f32 v145, v164, s[10:11] offset:0
	s_mov_b64 exec, s[18:19]
	s_add_u32 s98, s98, 0x8000
	s_addc_u32 s99, s99, 0
	ds_write_b128 v140, v[108:111]
	ds_write_b128 v141, v[104:107]
	ds_write_b128 v140, v[100:103] offset:128
	ds_write_b128 v141, v[96:99] offset:128
	s_waitcnt lgkmcnt(0)
	ds_read_b128 v[146:149], v142
	ds_read_b128 v[150:153], v143
	ds_read_b128 v[154:157], v142 offset:128
	ds_read_b128 v[158:161], v143 offset:128
	s_waitcnt vmcnt(15)
	s_waitcnt lgkmcnt(0)
	v_lshlrev_b32_e32 v162, 16, v196
	v_and_b32_e32 v163, 0xffff0000, v196
	v_lshlrev_b32_e32 v164, 16, v197
	v_and_b32_e32 v165, 0xffff0000, v197
	v_lshlrev_b32_e32 v166, 16, v198
	v_and_b32_e32 v167, 0xffff0000, v198
	v_lshlrev_b32_e32 v168, 16, v199
	v_and_b32_e32 v169, 0xffff0000, v199
	v_pk_add_f32 v[146:147], v[146:147], v[162:163]
	v_pk_add_f32 v[148:149], v[148:149], v[164:165]
	v_pk_add_f32 v[150:151], v[150:151], v[166:167]
	v_pk_add_f32 v[152:153], v[152:153], v[168:169]
	v_pk_mul_f32 v[170:171], v[146:147], v[146:147]
	v_pk_fma_f32 v[170:171], v[148:149], v[148:149], v[170:171]
	v_pk_fma_f32 v[170:171], v[150:151], v[150:151], v[170:171]
	v_pk_fma_f32 v[170:171], v[152:153], v[152:153], v[170:171]
	v_cvt_pk_bf16_f32 v172, v146, v147
	v_cvt_pk_bf16_f32 v173, v148, v149
	v_cvt_pk_bf16_f32 v174, v150, v151
	v_cvt_pk_bf16_f32 v175, v152, v153
	global_store_dwordx4 v144, v[172:175], s[98:99]
	v_lshlrev_b32_e32 v162, 16, v200
	v_and_b32_e32 v163, 0xffff0000, v200
	v_lshlrev_b32_e32 v164, 16, v201
	v_and_b32_e32 v165, 0xffff0000, v201
	v_lshlrev_b32_e32 v166, 16, v202
	v_and_b32_e32 v167, 0xffff0000, v202
	v_lshlrev_b32_e32 v168, 16, v203
	v_and_b32_e32 v169, 0xffff0000, v203
	v_pk_add_f32 v[154:155], v[154:155], v[162:163]
	v_pk_add_f32 v[156:157], v[156:157], v[164:165]
	v_pk_add_f32 v[158:159], v[158:159], v[166:167]
	v_pk_add_f32 v[160:161], v[160:161], v[168:169]
	v_pk_fma_f32 v[170:171], v[154:155], v[154:155], v[170:171]
	v_pk_fma_f32 v[170:171], v[156:157], v[156:157], v[170:171]
	v_pk_fma_f32 v[170:171], v[158:159], v[158:159], v[170:171]
	v_pk_fma_f32 v[170:171], v[160:161], v[160:161], v[170:171]
	v_cvt_pk_bf16_f32 v176, v154, v155
	v_cvt_pk_bf16_f32 v177, v156, v157
	v_cvt_pk_bf16_f32 v178, v158, v159
	v_cvt_pk_bf16_f32 v179, v160, v161
	global_store_dwordx4 v144, v[176:179], s[98:99] offset:256
	v_add_f32_e32 v162, v170, v171
	s_nop 1
	v_add_f32_dpp v163, v162, v162 quad_perm:[1,0,3,2] row_mask:0xf bank_mask:0xf
	s_nop 1
	v_add_f32_dpp v164, v163, v163 quad_perm:[2,3,0,1] row_mask:0xf bank_mask:0xf
	s_mov_b64 exec, vcc
	global_atomic_add_f32 v145, v164, s[10:11] offset:64
	s_mov_b64 exec, s[18:19]
	s_add_u32 s98, s98, 0x8000
	s_addc_u32 s99, s99, 0
	ds_write_b128 v140, v[92:95]
	ds_write_b128 v141, v[88:91]
	ds_write_b128 v140, v[84:87] offset:128
	ds_write_b128 v141, v[80:83] offset:128
	s_waitcnt lgkmcnt(0)
	ds_read_b128 v[146:149], v142
	ds_read_b128 v[150:153], v143
	ds_read_b128 v[154:157], v142 offset:128
	ds_read_b128 v[158:161], v143 offset:128
	s_waitcnt vmcnt(16)
	s_waitcnt lgkmcnt(0)
	v_lshlrev_b32_e32 v162, 16, v204
	v_and_b32_e32 v163, 0xffff0000, v204
	v_lshlrev_b32_e32 v164, 16, v205
	v_and_b32_e32 v165, 0xffff0000, v205
	v_lshlrev_b32_e32 v166, 16, v206
	v_and_b32_e32 v167, 0xffff0000, v206
	v_lshlrev_b32_e32 v168, 16, v207
	v_and_b32_e32 v169, 0xffff0000, v207
	v_pk_add_f32 v[146:147], v[146:147], v[162:163]
	v_pk_add_f32 v[148:149], v[148:149], v[164:165]
	v_pk_add_f32 v[150:151], v[150:151], v[166:167]
	v_pk_add_f32 v[152:153], v[152:153], v[168:169]
	v_pk_mul_f32 v[170:171], v[146:147], v[146:147]
	v_pk_fma_f32 v[170:171], v[148:149], v[148:149], v[170:171]
	v_pk_fma_f32 v[170:171], v[150:151], v[150:151], v[170:171]
	v_pk_fma_f32 v[170:171], v[152:153], v[152:153], v[170:171]
	v_cvt_pk_bf16_f32 v172, v146, v147
	v_cvt_pk_bf16_f32 v173, v148, v149
	v_cvt_pk_bf16_f32 v174, v150, v151
	v_cvt_pk_bf16_f32 v175, v152, v153
	global_store_dwordx4 v144, v[172:175], s[98:99]
	v_lshlrev_b32_e32 v162, 16, v208
	v_and_b32_e32 v163, 0xffff0000, v208
	v_lshlrev_b32_e32 v164, 16, v209
	v_and_b32_e32 v165, 0xffff0000, v209
	v_lshlrev_b32_e32 v166, 16, v210
	v_and_b32_e32 v167, 0xffff0000, v210
	v_lshlrev_b32_e32 v168, 16, v211
	v_and_b32_e32 v169, 0xffff0000, v211
	v_pk_add_f32 v[154:155], v[154:155], v[162:163]
	v_pk_add_f32 v[156:157], v[156:157], v[164:165]
	v_pk_add_f32 v[158:159], v[158:159], v[166:167]
	v_pk_add_f32 v[160:161], v[160:161], v[168:169]
	v_pk_fma_f32 v[170:171], v[154:155], v[154:155], v[170:171]
	v_pk_fma_f32 v[170:171], v[156:157], v[156:157], v[170:171]
	v_pk_fma_f32 v[170:171], v[158:159], v[158:159], v[170:171]
	v_pk_fma_f32 v[170:171], v[160:161], v[160:161], v[170:171]
	v_cvt_pk_bf16_f32 v176, v154, v155
	v_cvt_pk_bf16_f32 v177, v156, v157
	v_cvt_pk_bf16_f32 v178, v158, v159
	v_cvt_pk_bf16_f32 v179, v160, v161
	global_store_dwordx4 v144, v[176:179], s[98:99] offset:256
	v_add_f32_e32 v162, v170, v171
	s_nop 1
	v_add_f32_dpp v163, v162, v162 quad_perm:[1,0,3,2] row_mask:0xf bank_mask:0xf
	s_nop 1
	v_add_f32_dpp v164, v163, v163 quad_perm:[2,3,0,1] row_mask:0xf bank_mask:0xf
	s_mov_b64 exec, vcc
	global_atomic_add_f32 v145, v164, s[10:11] offset:128
	s_mov_b64 exec, s[18:19]
	s_add_u32 s98, s98, 0x8000
	s_addc_u32 s99, s99, 0
	ds_write_b128 v140, v[76:79]
	ds_write_b128 v141, v[72:75]
	ds_write_b128 v140, v[68:71] offset:128
	ds_write_b128 v141, v[64:67] offset:128
	s_waitcnt lgkmcnt(0)
	ds_read_b128 v[146:149], v142
	ds_read_b128 v[150:153], v143
	ds_read_b128 v[154:157], v142 offset:128
	ds_read_b128 v[158:161], v143 offset:128
	s_waitcnt vmcnt(17)
	s_waitcnt lgkmcnt(0)
	v_lshlrev_b32_e32 v162, 16, v212
	v_and_b32_e32 v163, 0xffff0000, v212
	v_lshlrev_b32_e32 v164, 16, v213
	v_and_b32_e32 v165, 0xffff0000, v213
	v_lshlrev_b32_e32 v166, 16, v214
	v_and_b32_e32 v167, 0xffff0000, v214
	v_lshlrev_b32_e32 v168, 16, v215
	v_and_b32_e32 v169, 0xffff0000, v215
	v_pk_add_f32 v[146:147], v[146:147], v[162:163]
	v_pk_add_f32 v[148:149], v[148:149], v[164:165]
	v_pk_add_f32 v[150:151], v[150:151], v[166:167]
	v_pk_add_f32 v[152:153], v[152:153], v[168:169]
	v_pk_mul_f32 v[170:171], v[146:147], v[146:147]
	v_pk_fma_f32 v[170:171], v[148:149], v[148:149], v[170:171]
	v_pk_fma_f32 v[170:171], v[150:151], v[150:151], v[170:171]
	v_pk_fma_f32 v[170:171], v[152:153], v[152:153], v[170:171]
	v_cvt_pk_bf16_f32 v172, v146, v147
	v_cvt_pk_bf16_f32 v173, v148, v149
	v_cvt_pk_bf16_f32 v174, v150, v151
	v_cvt_pk_bf16_f32 v175, v152, v153
	global_store_dwordx4 v144, v[172:175], s[98:99]
	v_lshlrev_b32_e32 v162, 16, v216
	v_and_b32_e32 v163, 0xffff0000, v216
	v_lshlrev_b32_e32 v164, 16, v217
	v_and_b32_e32 v165, 0xffff0000, v217
	v_lshlrev_b32_e32 v166, 16, v218
	v_and_b32_e32 v167, 0xffff0000, v218
	v_lshlrev_b32_e32 v168, 16, v219
	v_and_b32_e32 v169, 0xffff0000, v219
	v_pk_add_f32 v[154:155], v[154:155], v[162:163]
	v_pk_add_f32 v[156:157], v[156:157], v[164:165]
	v_pk_add_f32 v[158:159], v[158:159], v[166:167]
	v_pk_add_f32 v[160:161], v[160:161], v[168:169]
	v_pk_fma_f32 v[170:171], v[154:155], v[154:155], v[170:171]
	v_pk_fma_f32 v[170:171], v[156:157], v[156:157], v[170:171]
	v_pk_fma_f32 v[170:171], v[158:159], v[158:159], v[170:171]
	v_pk_fma_f32 v[170:171], v[160:161], v[160:161], v[170:171]
	v_cvt_pk_bf16_f32 v176, v154, v155
	v_cvt_pk_bf16_f32 v177, v156, v157
	v_cvt_pk_bf16_f32 v178, v158, v159
	v_cvt_pk_bf16_f32 v179, v160, v161
	global_store_dwordx4 v144, v[176:179], s[98:99] offset:256
	v_add_f32_e32 v162, v170, v171
	s_nop 1
	v_add_f32_dpp v163, v162, v162 quad_perm:[1,0,3,2] row_mask:0xf bank_mask:0xf
	s_nop 1
	v_add_f32_dpp v164, v163, v163 quad_perm:[2,3,0,1] row_mask:0xf bank_mask:0xf
	s_mov_b64 exec, vcc
	global_atomic_add_f32 v145, v164, s[10:11] offset:192
	s_mov_b64 exec, s[18:19]
	s_add_u32 s98, s98, 0x28000
	s_addc_u32 s99, s99, 0
	ds_write_b128 v140, v[60:63]
	ds_write_b128 v141, v[56:59]
	ds_write_b128 v140, v[52:55] offset:128
	ds_write_b128 v141, v[48:51] offset:128
	s_waitcnt lgkmcnt(0)
	ds_read_b128 v[146:149], v142
	ds_read_b128 v[150:153], v143
	ds_read_b128 v[154:157], v142 offset:128
	ds_read_b128 v[158:161], v143 offset:128
	s_waitcnt vmcnt(18)
	s_waitcnt lgkmcnt(0)
	v_lshlrev_b32_e32 v162, 16, v220
	v_and_b32_e32 v163, 0xffff0000, v220
	v_lshlrev_b32_e32 v164, 16, v221
	v_and_b32_e32 v165, 0xffff0000, v221
	v_lshlrev_b32_e32 v166, 16, v222
	v_and_b32_e32 v167, 0xffff0000, v222
	v_lshlrev_b32_e32 v168, 16, v223
	v_and_b32_e32 v169, 0xffff0000, v223
	v_pk_add_f32 v[146:147], v[146:147], v[162:163]
	v_pk_add_f32 v[148:149], v[148:149], v[164:165]
	v_pk_add_f32 v[150:151], v[150:151], v[166:167]
	v_pk_add_f32 v[152:153], v[152:153], v[168:169]
	v_pk_mul_f32 v[170:171], v[146:147], v[146:147]
	v_pk_fma_f32 v[170:171], v[148:149], v[148:149], v[170:171]
	v_pk_fma_f32 v[170:171], v[150:151], v[150:151], v[170:171]
	v_pk_fma_f32 v[170:171], v[152:153], v[152:153], v[170:171]
	v_cvt_pk_bf16_f32 v172, v146, v147
	v_cvt_pk_bf16_f32 v173, v148, v149
	v_cvt_pk_bf16_f32 v174, v150, v151
	v_cvt_pk_bf16_f32 v175, v152, v153
	global_store_dwordx4 v144, v[172:175], s[98:99]
	v_lshlrev_b32_e32 v162, 16, v224
	v_and_b32_e32 v163, 0xffff0000, v224
	v_lshlrev_b32_e32 v164, 16, v225
	v_and_b32_e32 v165, 0xffff0000, v225
	v_lshlrev_b32_e32 v166, 16, v226
	v_and_b32_e32 v167, 0xffff0000, v226
	v_lshlrev_b32_e32 v168, 16, v227
	v_and_b32_e32 v169, 0xffff0000, v227
	v_pk_add_f32 v[154:155], v[154:155], v[162:163]
	v_pk_add_f32 v[156:157], v[156:157], v[164:165]
	v_pk_add_f32 v[158:159], v[158:159], v[166:167]
	v_pk_add_f32 v[160:161], v[160:161], v[168:169]
	v_pk_fma_f32 v[170:171], v[154:155], v[154:155], v[170:171]
	v_pk_fma_f32 v[170:171], v[156:157], v[156:157], v[170:171]
	v_pk_fma_f32 v[170:171], v[158:159], v[158:159], v[170:171]
	v_pk_fma_f32 v[170:171], v[160:161], v[160:161], v[170:171]
	v_cvt_pk_bf16_f32 v176, v154, v155
	v_cvt_pk_bf16_f32 v177, v156, v157
	v_cvt_pk_bf16_f32 v178, v158, v159
	v_cvt_pk_bf16_f32 v179, v160, v161
	global_store_dwordx4 v144, v[176:179], s[98:99] offset:256
	v_add_f32_e32 v162, v170, v171
	s_nop 1
	v_add_f32_dpp v163, v162, v162 quad_perm:[1,0,3,2] row_mask:0xf bank_mask:0xf
	s_nop 1
	v_add_f32_dpp v164, v163, v163 quad_perm:[2,3,0,1] row_mask:0xf bank_mask:0xf
	s_mov_b64 exec, vcc
	global_atomic_add_f32 v145, v164, s[10:11] offset:512
	s_mov_b64 exec, s[18:19]
	s_add_u32 s98, s98, 0x8000
	s_addc_u32 s99, s99, 0
	ds_write_b128 v140, v[44:47]
	ds_write_b128 v141, v[40:43]
	ds_write_b128 v140, v[36:39] offset:128
	ds_write_b128 v141, v[32:35] offset:128
	s_waitcnt lgkmcnt(0)
	ds_read_b128 v[146:149], v142
	ds_read_b128 v[150:153], v143
	ds_read_b128 v[154:157], v142 offset:128
	ds_read_b128 v[158:161], v143 offset:128
	s_waitcnt vmcnt(19)
	s_waitcnt lgkmcnt(0)
	v_lshlrev_b32_e32 v162, 16, v228
	v_and_b32_e32 v163, 0xffff0000, v228
	v_lshlrev_b32_e32 v164, 16, v229
	v_and_b32_e32 v165, 0xffff0000, v229
	v_lshlrev_b32_e32 v166, 16, v230
	v_and_b32_e32 v167, 0xffff0000, v230
	v_lshlrev_b32_e32 v168, 16, v231
	v_and_b32_e32 v169, 0xffff0000, v231
	v_pk_add_f32 v[146:147], v[146:147], v[162:163]
	v_pk_add_f32 v[148:149], v[148:149], v[164:165]
	v_pk_add_f32 v[150:151], v[150:151], v[166:167]
	v_pk_add_f32 v[152:153], v[152:153], v[168:169]
	v_pk_mul_f32 v[170:171], v[146:147], v[146:147]
	v_pk_fma_f32 v[170:171], v[148:149], v[148:149], v[170:171]
	v_pk_fma_f32 v[170:171], v[150:151], v[150:151], v[170:171]
	v_pk_fma_f32 v[170:171], v[152:153], v[152:153], v[170:171]
	v_cvt_pk_bf16_f32 v172, v146, v147
	v_cvt_pk_bf16_f32 v173, v148, v149
	v_cvt_pk_bf16_f32 v174, v150, v151
	v_cvt_pk_bf16_f32 v175, v152, v153
	global_store_dwordx4 v144, v[172:175], s[98:99]
	v_lshlrev_b32_e32 v162, 16, v232
	v_and_b32_e32 v163, 0xffff0000, v232
	v_lshlrev_b32_e32 v164, 16, v233
	v_and_b32_e32 v165, 0xffff0000, v233
	v_lshlrev_b32_e32 v166, 16, v234
	v_and_b32_e32 v167, 0xffff0000, v234
	v_lshlrev_b32_e32 v168, 16, v235
	v_and_b32_e32 v169, 0xffff0000, v235
	v_pk_add_f32 v[154:155], v[154:155], v[162:163]
	v_pk_add_f32 v[156:157], v[156:157], v[164:165]
	v_pk_add_f32 v[158:159], v[158:159], v[166:167]
	v_pk_add_f32 v[160:161], v[160:161], v[168:169]
	v_pk_fma_f32 v[170:171], v[154:155], v[154:155], v[170:171]
	v_pk_fma_f32 v[170:171], v[156:157], v[156:157], v[170:171]
	v_pk_fma_f32 v[170:171], v[158:159], v[158:159], v[170:171]
	v_pk_fma_f32 v[170:171], v[160:161], v[160:161], v[170:171]
	v_cvt_pk_bf16_f32 v176, v154, v155
	v_cvt_pk_bf16_f32 v177, v156, v157
	v_cvt_pk_bf16_f32 v178, v158, v159
	v_cvt_pk_bf16_f32 v179, v160, v161
	global_store_dwordx4 v144, v[176:179], s[98:99] offset:256
	v_add_f32_e32 v162, v170, v171
	s_nop 1
	v_add_f32_dpp v163, v162, v162 quad_perm:[1,0,3,2] row_mask:0xf bank_mask:0xf
	s_nop 1
	v_add_f32_dpp v164, v163, v163 quad_perm:[2,3,0,1] row_mask:0xf bank_mask:0xf
	s_mov_b64 exec, vcc
	global_atomic_add_f32 v145, v164, s[10:11] offset:576
	s_mov_b64 exec, s[18:19]
	s_add_u32 s98, s98, 0x8000
	s_addc_u32 s99, s99, 0
	ds_write_b128 v140, v[28:31]
	ds_write_b128 v141, v[24:27]
	ds_write_b128 v140, v[20:23] offset:128
	ds_write_b128 v141, v[16:19] offset:128
	s_waitcnt lgkmcnt(0)
	ds_read_b128 v[146:149], v142
	ds_read_b128 v[150:153], v143
	ds_read_b128 v[154:157], v142 offset:128
	ds_read_b128 v[158:161], v143 offset:128
	s_waitcnt vmcnt(20)
	s_waitcnt lgkmcnt(0)
	v_lshlrev_b32_e32 v162, 16, v236
	v_and_b32_e32 v163, 0xffff0000, v236
	v_lshlrev_b32_e32 v164, 16, v237
	v_and_b32_e32 v165, 0xffff0000, v237
	v_lshlrev_b32_e32 v166, 16, v238
	v_and_b32_e32 v167, 0xffff0000, v238
	v_lshlrev_b32_e32 v168, 16, v239
	v_and_b32_e32 v169, 0xffff0000, v239
	v_pk_add_f32 v[146:147], v[146:147], v[162:163]
	v_pk_add_f32 v[148:149], v[148:149], v[164:165]
	v_pk_add_f32 v[150:151], v[150:151], v[166:167]
	v_pk_add_f32 v[152:153], v[152:153], v[168:169]
	v_pk_mul_f32 v[170:171], v[146:147], v[146:147]
	v_pk_fma_f32 v[170:171], v[148:149], v[148:149], v[170:171]
	v_pk_fma_f32 v[170:171], v[150:151], v[150:151], v[170:171]
	v_pk_fma_f32 v[170:171], v[152:153], v[152:153], v[170:171]
	v_cvt_pk_bf16_f32 v172, v146, v147
	v_cvt_pk_bf16_f32 v173, v148, v149
	v_cvt_pk_bf16_f32 v174, v150, v151
	v_cvt_pk_bf16_f32 v175, v152, v153
	global_store_dwordx4 v144, v[172:175], s[98:99]
	v_lshlrev_b32_e32 v162, 16, v240
	v_and_b32_e32 v163, 0xffff0000, v240
	v_lshlrev_b32_e32 v164, 16, v241
	v_and_b32_e32 v165, 0xffff0000, v241
	v_lshlrev_b32_e32 v166, 16, v242
	v_and_b32_e32 v167, 0xffff0000, v242
	v_lshlrev_b32_e32 v168, 16, v243
	v_and_b32_e32 v169, 0xffff0000, v243
	v_pk_add_f32 v[154:155], v[154:155], v[162:163]
	v_pk_add_f32 v[156:157], v[156:157], v[164:165]
	v_pk_add_f32 v[158:159], v[158:159], v[166:167]
	v_pk_add_f32 v[160:161], v[160:161], v[168:169]
	v_pk_fma_f32 v[170:171], v[154:155], v[154:155], v[170:171]
	v_pk_fma_f32 v[170:171], v[156:157], v[156:157], v[170:171]
	v_pk_fma_f32 v[170:171], v[158:159], v[158:159], v[170:171]
	v_pk_fma_f32 v[170:171], v[160:161], v[160:161], v[170:171]
	v_cvt_pk_bf16_f32 v176, v154, v155
	v_cvt_pk_bf16_f32 v177, v156, v157
	v_cvt_pk_bf16_f32 v178, v158, v159
	v_cvt_pk_bf16_f32 v179, v160, v161
	global_store_dwordx4 v144, v[176:179], s[98:99] offset:256
	v_add_f32_e32 v162, v170, v171
	s_nop 1
	v_add_f32_dpp v163, v162, v162 quad_perm:[1,0,3,2] row_mask:0xf bank_mask:0xf
	s_nop 1
	v_add_f32_dpp v164, v163, v163 quad_perm:[2,3,0,1] row_mask:0xf bank_mask:0xf
	s_mov_b64 exec, vcc
	global_atomic_add_f32 v145, v164, s[10:11] offset:640
	s_mov_b64 exec, s[18:19]
	s_add_u32 s98, s98, 0x8000
	s_addc_u32 s99, s99, 0
	ds_write_b128 v140, v[12:15]
	ds_write_b128 v141, v[8:11]
	ds_write_b128 v140, v[4:7] offset:128
	ds_write_b128 v141, v[0:3] offset:128
	s_waitcnt lgkmcnt(0)
	ds_read_b128 v[146:149], v142
	ds_read_b128 v[150:153], v143
	ds_read_b128 v[154:157], v142 offset:128
	ds_read_b128 v[158:161], v143 offset:128
	s_waitcnt vmcnt(21)
	s_waitcnt lgkmcnt(0)
	v_lshlrev_b32_e32 v162, 16, v244
	v_and_b32_e32 v163, 0xffff0000, v244
	v_lshlrev_b32_e32 v164, 16, v245
	v_and_b32_e32 v165, 0xffff0000, v245
	v_lshlrev_b32_e32 v166, 16, v246
	v_and_b32_e32 v167, 0xffff0000, v246
	v_lshlrev_b32_e32 v168, 16, v247
	v_and_b32_e32 v169, 0xffff0000, v247
	v_pk_add_f32 v[146:147], v[146:147], v[162:163]
	v_pk_add_f32 v[148:149], v[148:149], v[164:165]
	v_pk_add_f32 v[150:151], v[150:151], v[166:167]
	v_pk_add_f32 v[152:153], v[152:153], v[168:169]
	v_pk_mul_f32 v[170:171], v[146:147], v[146:147]
	v_pk_fma_f32 v[170:171], v[148:149], v[148:149], v[170:171]
	v_pk_fma_f32 v[170:171], v[150:151], v[150:151], v[170:171]
	v_pk_fma_f32 v[170:171], v[152:153], v[152:153], v[170:171]
	v_cvt_pk_bf16_f32 v172, v146, v147
	v_cvt_pk_bf16_f32 v173, v148, v149
	v_cvt_pk_bf16_f32 v174, v150, v151
	v_cvt_pk_bf16_f32 v175, v152, v153
	global_store_dwordx4 v144, v[172:175], s[98:99]
	v_lshlrev_b32_e32 v162, 16, v248
	v_and_b32_e32 v163, 0xffff0000, v248
	v_lshlrev_b32_e32 v164, 16, v249
	v_and_b32_e32 v165, 0xffff0000, v249
	v_lshlrev_b32_e32 v166, 16, v250
	v_and_b32_e32 v167, 0xffff0000, v250
	v_lshlrev_b32_e32 v168, 16, v251
	v_and_b32_e32 v169, 0xffff0000, v251
	v_pk_add_f32 v[154:155], v[154:155], v[162:163]
	v_pk_add_f32 v[156:157], v[156:157], v[164:165]
	v_pk_add_f32 v[158:159], v[158:159], v[166:167]
	v_pk_add_f32 v[160:161], v[160:161], v[168:169]
	v_pk_fma_f32 v[170:171], v[154:155], v[154:155], v[170:171]
	v_pk_fma_f32 v[170:171], v[156:157], v[156:157], v[170:171]
	v_pk_fma_f32 v[170:171], v[158:159], v[158:159], v[170:171]
	v_pk_fma_f32 v[170:171], v[160:161], v[160:161], v[170:171]
	v_cvt_pk_bf16_f32 v176, v154, v155
	v_cvt_pk_bf16_f32 v177, v156, v157
	v_cvt_pk_bf16_f32 v178, v158, v159
	v_cvt_pk_bf16_f32 v179, v160, v161
	global_store_dwordx4 v144, v[176:179], s[98:99] offset:256
	v_add_f32_e32 v162, v170, v171
	s_nop 1
	v_add_f32_dpp v163, v162, v162 quad_perm:[1,0,3,2] row_mask:0xf bank_mask:0xf
	s_nop 1
	v_add_f32_dpp v164, v163, v163 quad_perm:[2,3,0,1] row_mask:0xf bank_mask:0xf
	s_mov_b64 exec, vcc
	global_atomic_add_f32 v145, v164, s[10:11] offset:704
	s_mov_b64 exec, s[18:19]

	.amdhsa_kernel _Z10fwd_kernel6Params
		.amdhsa_group_segment_fixed_size 32768
		.amdhsa_private_segment_fixed_size 0
		.amdhsa_kernarg_size 560
		.amdhsa_user_sgpr_count 2
		.amdhsa_user_sgpr_dispatch_ptr 0
		.amdhsa_user_sgpr_queue_ptr 0
		.amdhsa_user_sgpr_kernarg_segment_ptr 1
		.amdhsa_user_sgpr_dispatch_id 0
		.amdhsa_user_sgpr_kernarg_preload_length 0
		.amdhsa_user_sgpr_kernarg_preload_offset 0
		.amdhsa_user_sgpr_private_segment_size 0
		.amdhsa_uses_dynamic_stack 0
		.amdhsa_enable_private_segment 0
		.amdhsa_system_sgpr_workgroup_id_x 1
		.amdhsa_system_sgpr_workgroup_id_y 0
		.amdhsa_system_sgpr_workgroup_id_z 0
		.amdhsa_system_sgpr_workgroup_info 0
		.amdhsa_system_vgpr_workitem_id 2
		.amdhsa_next_free_vgpr 256
		.amdhsa_next_free_sgpr 102
		.amdhsa_accum_offset 256
		.amdhsa_reserve_vcc 1
		.amdhsa_float_round_mode_32 0
		.amdhsa_float_round_mode_16_64 0
		.amdhsa_float_denorm_mode_32 3
		.amdhsa_float_denorm_mode_16_64 3
		.amdhsa_dx10_clamp 1
		.amdhsa_ieee_mode 1
		.amdhsa_fp16_overflow 0
		.amdhsa_tg_split 0
		.amdhsa_exception_fp_ieee_invalid_op 0
		.amdhsa_exception_fp_denorm_src 0
		.amdhsa_exception_fp_ieee_div_zero 0
		.amdhsa_exception_fp_ieee_overflow 0
		.amdhsa_exception_fp_ieee_underflow 0
		.amdhsa_exception_fp_ieee_inexact 0
		.amdhsa_exception_int_div_zero 0
	.end_amdhsa_kernel

amdhsa.kernels:
  - .agpr_count:     0
    .args:
      - .offset:         0
        .size:           304
        .value_kind:     by_value
      - .offset:         304
        .size:           4
        .value_kind:     hidden_block_count_x
      - .offset:         308
        .size:           4
        .value_kind:     hidden_block_count_y
      - .offset:         312
        .size:           4
        .value_kind:     hidden_block_count_z
      - .offset:         316
        .size:           2
        .value_kind:     hidden_group_size_x
      - .offset:         318
        .size:           2
        .value_kind:     hidden_group_size_y
      - .offset:         320
        .size:           2
        .value_kind:     hidden_group_size_z
      - .offset:         322
        .size:           2
        .value_kind:     hidden_remainder_x
      - .offset:         324
        .size:           2
        .value_kind:     hidden_remainder_y
      - .offset:         326
        .size:           2
        .value_kind:     hidden_remainder_z
      - .offset:         344
        .size:           8
        .value_kind:     hidden_global_offset_x
      - .offset:         352
        .size:           8
        .value_kind:     hidden_global_offset_y
      - .offset:         360
        .size:           8
        .value_kind:     hidden_global_offset_z
      - .offset:         368
        .size:           2
        .value_kind:     hidden_grid_dims
      - .offset:         392
        .size:           8
        .value_kind:     hidden_multigrid_sync_arg
      - .offset:         424
        .size:           4
        .value_kind:     hidden_dynamic_lds_size
    .group_segment_fixed_size: 32768
    .kernarg_segment_align: 8
    .kernarg_segment_size: 560
    .language:       OpenCL C
    .language_version:
      - 2
      - 0
    .max_flat_workgroup_size: 512
    .name:           _Z10fwd_kernel6Params
    .private_segment_fixed_size: 0
    .sgpr_count:     108
    .sgpr_spill_count: 143
    .symbol:         _Z10fwd_kernel6Params.kd
    .uniform_work_group_size: 1
    .uses_dynamic_stack: false
    .vgpr_count:     256
    .vgpr_spill_count: 0
    .wavefront_size: 64
